# K1+C plus: removed s_setprio flips around the MFMA blocks of the GEMM K-loops
# baseline (speedup 1.0000x reference)
; #define PG8_STAGE(bufoff, gbase, voff) do { _Pragma("unroll") for (int _i = 0; _i < 2; ++_i) \
;         __builtin_amdgcn_global_load_lds((const unsigned*)((const char*)(gbase) + (voff)[_i]), (PG8_LAS unsigned*)(lds + (bufoff) + ldsw + _i * 8192), 16, 0, 0); } while (0)
; #define PG8_LDA(dst, b, h) do { _Pragma("unroll") for (int m = 0; m < 4; ++m) _Pragma("unroll") for (int k = 0; k < 2; ++k) dst[m][k] = *(const PG8_LAS bf16x8*)(lds + PG8_SA(b, h) + aoff + m * 2048 + k * 1024); } while (0)
; template <class Epi, class Sched, bool ALIGN_EPI = false, bool SP2 = false>
; __device__ __forceinline__ void gemm_phase(PG8_LAS unsigned char* lds, const Gemm g, const Sched& S, const Epi& E) {
;     ...
;         const bool has_next = S.next(ui + 1, nxt);
;         const char* nA = has_next ? (const char*)g.A + (size_t)nxt.pm * tstep : cA; const char* nB = has_next ? (const char*)g.Bt + (size_t)nxt.pn * tstep : cB;
;         for (int t = 0; t < nt; t += 2) {
;             const bool last = (t == nt - 2);
;             const char* a1 = cA + (size_t)(t + 1) * kstep;
;             const char* a2 = last ? nA : cA + (size_t)(t + 2) * kstep; const char* b2 = last ? nB : cB + (size_t)(t + 2) * kstep;
;             const char* a3 = a2 + kstep; const char* b3 = b2 + kstep;
;             if (last && has_next) S.a_ready(nxt);
;             if constexpr (SP2) {
;             PG8_LDB(B0, 0, 0); PG8_LDB(B1, 0, 1); PG8_SCHED; PG8_LDA(At, 0, 0); PG8_STAGE(PG8_SA(1, 1), a1 + hstep, voffA);
;             PG8_WAIT_V(8); PG8_WAIT_L(0); PG8_BAR; PG8_MMA(0, 0, At, B0); PG8_MMA(0, 1, At, B1); PG8_BAR; PG8_SCHED;
;             PG8_LDA(At, 0, 1); PG8_STAGE(PG8_SB(0, 0), b2, voffB); PG8_STAGE(PG8_SB(0, 1), b2 + hstep, voffB); PG8_STAGE(PG8_SA(0, 0), a2, voffA);
;             PG8_WAIT_V(8); PG8_WAIT_L(0); PG8_BAR; PG8_MMA(1, 0, At, B0); PG8_MMA(1, 1, At, B1); PG8_BAR; PG8_SCHED;
;             PG8_LDB(B0, 1, 0); PG8_LDB(B1, 1, 1); PG8_SCHED; PG8_LDA(At, 1, 0); PG8_STAGE(PG8_SA(0, 1), a2 + hstep, voffA);
;             PG8_WAIT_V(8); PG8_WAIT_L(0); PG8_BAR; PG8_MMA(0, 0, At, B0); PG8_MMA(0, 1, At, B1); PG8_BAR; PG8_SCHED;
;             PG8_LDA(At, 1, 1); PG8_STAGE(PG8_SB(1, 0), b3, voffB); PG8_STAGE(PG8_SB(1, 1), b3 + hstep, voffB); PG8_STAGE(PG8_SA(1, 0), a3, voffA);
;             PG8_WAIT_V(8); PG8_WAIT_L(0); PG8_BAR; PG8_MMA(1, 0, At, B0); PG8_MMA(1, 1, At, B1); PG8_BAR; PG8_SCHED;
.LBB0_905:
	s_ashr_i32 s13, s12, 31
	s_lshl_b64 s[14:15], s[12:13], 17
	s_add_u32 s14, s22, s14
	s_addc_u32 s15, s23, s15
	s_and_b64 s[16:17], s[2:3], exec
	s_cselect_b32 s71, s15, s19
	s_cselect_b32 s70, s14, s18
	s_ashr_i32 s11, s10, 31
	s_lshl_b64 s[16:17], s[10:11], 17
	s_add_u32 s16, s27, s16
	s_addc_u32 s17, s28, s17
	s_and_b64 s[64:65], s[2:3], exec
	s_cselect_b32 s69, s17, s67
	s_cselect_b32 s68, s16, s66
	s_add_u32 s74, s18, 0x10000
	s_addc_u32 s75, s19, 0
	s_add_u32 s76, s66, 0x10000
	s_addc_u32 s77, s67, 0
	s_add_u32 s72, s18, 0x18000
	s_addc_u32 s73, s19, 0
	s_add_i32 s59, 0, 0x10000
	s_add_i32 s13, 0, 0x14000
	v_add_u32_e32 v202, s59, v206
	v_add_u32_e32 v203, s13, v206
	ds_read_b128 v[128:131], v202
	ds_read_b128 v[132:135], v202 offset:1024
	ds_read_b128 v[136:139], v202 offset:2048
	ds_read_b128 v[140:143], v202 offset:3072
	ds_read_b128 v[144:147], v203
	ds_read_b128 v[148:151], v203 offset:1024
	ds_read_b128 v[152:155], v203 offset:2048
	ds_read_b128 v[156:159], v203 offset:3072
	s_add_u32 s80, s18, 0xc000
	s_addc_u32 s81, s19, 0
	s_add_i32 s64, s33, 0xc000
	s_mov_b32 m0, s64
	s_add_i32 s5, s33, 0xe000
	ds_read_b128 v[168:171], v207
	ds_read_b128 v[172:175], v207 offset:1024
	ds_read_b128 v[176:179], v207 offset:2048
	ds_read_b128 v[180:183], v207 offset:3072
	ds_read_b128 v[184:187], v207 offset:4096
	ds_read_b128 v[188:191], v207 offset:5120
	ds_read_b128 v[192:195], v207 offset:6144
	ds_read_b128 v[196:199], v207 offset:7168
	global_load_lds_dwordx4 v160, s[80:81]
	s_mov_b32 m0, s5
	s_nop 0
	global_load_lds_dwordx4 v164, s[80:81]
	s_waitcnt vmcnt(8)
	s_waitcnt lgkmcnt(0)
	s_barrier
	s_waitcnt lgkmcnt(0)
	v_mfma_f32_16x16x32_bf16 v[124:127], v[128:131], v[168:171], v[124:127]
	v_mfma_f32_16x16x32_bf16 v[120:123], v[136:139], v[168:171], v[120:123]
	v_mfma_f32_16x16x32_bf16 v[116:119], v[128:131], v[176:179], v[116:119]
	v_mfma_f32_16x16x32_bf16 v[112:115], v[136:139], v[176:179], v[112:115]
	v_mfma_f32_16x16x32_bf16 v[108:111], v[128:131], v[184:187], v[108:111]
	v_mfma_f32_16x16x32_bf16 v[104:107], v[136:139], v[184:187], v[104:107]
	v_mfma_f32_16x16x32_bf16 v[100:103], v[128:131], v[192:195], v[100:103]
	v_mfma_f32_16x16x32_bf16 v[96:99], v[136:139], v[192:195], v[96:99]
	v_mfma_f32_16x16x32_bf16 v[124:127], v[132:135], v[172:175], v[124:127]
	v_mfma_f32_16x16x32_bf16 v[120:123], v[140:143], v[172:175], v[120:123]
	v_mfma_f32_16x16x32_bf16 v[116:119], v[132:135], v[180:183], v[116:119]
	v_mfma_f32_16x16x32_bf16 v[112:115], v[140:143], v[180:183], v[112:115]
	v_mfma_f32_16x16x32_bf16 v[108:111], v[132:135], v[188:191], v[108:111]
	v_mfma_f32_16x16x32_bf16 v[104:107], v[140:143], v[188:191], v[104:107]
	v_mfma_f32_16x16x32_bf16 v[100:103], v[132:135], v[196:199], v[100:103]
	v_mfma_f32_16x16x32_bf16 v[96:99], v[140:143], v[196:199], v[96:99]
	v_mfma_f32_16x16x32_bf16 v[92:95], v[144:147], v[168:171], v[92:95]
	v_mfma_f32_16x16x32_bf16 v[88:91], v[152:155], v[168:171], v[88:91]
	v_mfma_f32_16x16x32_bf16 v[84:87], v[144:147], v[176:179], v[84:87]
	v_mfma_f32_16x16x32_bf16 v[80:83], v[152:155], v[176:179], v[80:83]
	v_mfma_f32_16x16x32_bf16 v[76:79], v[144:147], v[184:187], v[76:79]
	v_mfma_f32_16x16x32_bf16 v[72:75], v[152:155], v[184:187], v[72:75]
	v_mfma_f32_16x16x32_bf16 v[68:71], v[144:147], v[192:195], v[68:71]
	v_mfma_f32_16x16x32_bf16 v[64:67], v[152:155], v[192:195], v[64:67]
	v_mfma_f32_16x16x32_bf16 v[92:95], v[148:151], v[172:175], v[92:95]
	v_mfma_f32_16x16x32_bf16 v[88:91], v[156:159], v[172:175], v[88:91]
	v_mfma_f32_16x16x32_bf16 v[84:87], v[148:151], v[180:183], v[84:87]
	v_mfma_f32_16x16x32_bf16 v[80:83], v[156:159], v[180:183], v[80:83]
	v_mfma_f32_16x16x32_bf16 v[76:79], v[148:151], v[188:191], v[76:79]
	v_mfma_f32_16x16x32_bf16 v[72:75], v[156:159], v[188:191], v[72:75]
	v_mfma_f32_16x16x32_bf16 v[68:71], v[148:151], v[196:199], v[68:71]
	v_mfma_f32_16x16x32_bf16 v[64:67], v[156:159], v[196:199], v[64:67]
	s_barrier
	s_add_i32 s59, s59, s30
	s_mov_b32 m0, s59
	s_add_i32 s11, s59, 0x2000
	ds_read_b128 v[168:171], v207 offset:16384
	ds_read_b128 v[172:175], v207 offset:17408
	ds_read_b128 v[176:179], v207 offset:18432
	ds_read_b128 v[180:183], v207 offset:19456
	ds_read_b128 v[184:187], v207 offset:20480
	ds_read_b128 v[188:191], v207 offset:21504
	ds_read_b128 v[192:195], v207 offset:22528
	ds_read_b128 v[196:199], v207 offset:23552
	global_load_lds_dwordx4 v162, s[76:77]
	v_lshl_add_u64 v[200:201], s[76:77], 0, v[166:167]
	s_add_u32 s76, s66, 0x14000
	s_mov_b32 m0, s11
	s_addc_u32 s77, s67, 0
	s_add_i32 s13, s13, s30
	global_load_lds_dwordx4 v[200:201], off
	s_mov_b32 m0, s13
	s_add_i32 s21, s13, 0x2000
	global_load_lds_dwordx4 v162, s[76:77]
	s_mov_b32 m0, s21
	s_nop 0
	global_load_lds_dwordx4 v166, s[76:77]
	s_mov_b32 m0, s33
	s_nop 0
	global_load_lds_dwordx4 v160, s[74:75]
	s_mov_b32 m0, s37
	s_nop 0
	global_load_lds_dwordx4 v164, s[74:75]
	s_waitcnt vmcnt(8)
	s_waitcnt lgkmcnt(0)
	s_barrier
; #define PG8_STAGE(bufoff, gbase, voff) do { _Pragma("unroll") for (int _i = 0; _i < 2; ++_i) \
;         __builtin_amdgcn_global_load_lds((const unsigned*)((const char*)(gbase) + (voff)[_i]), (PG8_LAS unsigned*)(lds + (bufoff) + ldsw + _i * 8192), 16, 0, 0); } while (0)
; #define PG8_LDA(dst, b, h) do { _Pragma("unroll") for (int m = 0; m < 4; ++m) _Pragma("unroll") for (int k = 0; k < 2; ++k) dst[m][k] = *(const PG8_LAS bf16x8*)(lds + PG8_SA(b, h) + aoff + m * 2048 + k * 1024); } while (0)
; #define PG8_LDB(dst, b, h) do { _Pragma("unroll") for (int n = 0; n < 2; ++n) _Pragma("unroll") for (int k = 0; k < 2; ++k) dst[n][k] = *(const PG8_LAS bf16x8*)(lds + PG8_SB(b, h) + boff + n * 2048 + k * 1024); } while (0)
; #define PG8_MMA(ai, bj, At, Bt) do { __builtin_amdgcn_s_setprio(1); _Pragma("unroll") for (int m = 0; m < 4; ++m) _Pragma("unroll") for (int n = 0; n < 2; ++n) _Pragma("unroll") for (int k = 0; k < 2; ++k) \
;         acc[ai][bj][m][n] = __builtin_amdgcn_mfma_f32_16x16x32_bf16(Bt[n][k], At[m][k], acc[ai][bj][m][n], 0, 0, 0); __builtin_amdgcn_s_setprio(0); } while (0)
; #define PG8_WAIT_V(n) asm volatile("s_waitcnt vmcnt(" #n ")" ::: "memory")
; template <class Epi, class Sched, bool ALIGN_EPI = false, bool SP2 = false>
; __device__ __forceinline__ void gemm_phase(PG8_LAS unsigned char* lds, const Gemm g, const Sched& S, const Epi& E) {
;     ...
;             PG8_LDB(B0, 0, 0); PG8_LDB(B1, 0, 1); PG8_SCHED; PG8_LDA(At, 0, 0); PG8_STAGE(PG8_SA(1, 1), a1 + hstep, voffA);
;             PG8_WAIT_V(8); PG8_WAIT_L(0); PG8_BAR; PG8_MMA(0, 0, At, B0); PG8_MMA(0, 1, At, B1); PG8_BAR; PG8_SCHED;
;             PG8_LDA(At, 0, 1); PG8_STAGE(PG8_SB(0, 0), b2, voffB); PG8_STAGE(PG8_SB(0, 1), b2 + hstep, voffB); PG8_STAGE(PG8_SA(0, 0), a2, voffA);
;             PG8_WAIT_V(8); PG8_WAIT_L(0); PG8_BAR; PG8_MMA(1, 0, At, B0); PG8_MMA(1, 1, At, B1); PG8_BAR; PG8_SCHED;
;             PG8_LDB(B0, 1, 0); PG8_LDB(B1, 1, 1); PG8_SCHED; PG8_LDA(At, 1, 0); PG8_STAGE(PG8_SA(0, 1), a2 + hstep, voffA);
;             PG8_WAIT_V(8); PG8_WAIT_L(0); PG8_BAR; PG8_MMA(0, 0, At, B0); PG8_MMA(0, 1, At, B1); PG8_BAR; PG8_SCHED;
;             PG8_LDA(At, 1, 1); PG8_STAGE(PG8_SB(1, 0), b3, voffB); PG8_STAGE(PG8_SB(1, 1), b3 + hstep, voffB); PG8_STAGE(PG8_SA(1, 0), a3, voffA);
;             PG8_WAIT_V(8); PG8_WAIT_L(0); PG8_BAR; PG8_MMA(1, 0, At, B0); PG8_MMA(1, 1, At, B1); PG8_BAR; PG8_SCHED;
	s_waitcnt lgkmcnt(0)
	v_mfma_f32_16x16x32_bf16 v[60:63], v[128:131], v[168:171], v[60:63]
	v_mfma_f32_16x16x32_bf16 v[56:59], v[136:139], v[168:171], v[56:59]
	v_mfma_f32_16x16x32_bf16 v[52:55], v[128:131], v[176:179], v[52:55]
	v_mfma_f32_16x16x32_bf16 v[48:51], v[136:139], v[176:179], v[48:51]
	v_mfma_f32_16x16x32_bf16 v[44:47], v[128:131], v[184:187], v[44:47]
	v_mfma_f32_16x16x32_bf16 v[40:43], v[136:139], v[184:187], v[40:43]
	v_mfma_f32_16x16x32_bf16 v[36:39], v[128:131], v[192:195], v[36:39]
	v_mfma_f32_16x16x32_bf16 v[32:35], v[136:139], v[192:195], v[32:35]
	v_mfma_f32_16x16x32_bf16 v[60:63], v[132:135], v[172:175], v[60:63]
	v_mfma_f32_16x16x32_bf16 v[56:59], v[140:143], v[172:175], v[56:59]
	v_mfma_f32_16x16x32_bf16 v[52:55], v[132:135], v[180:183], v[52:55]
	v_mfma_f32_16x16x32_bf16 v[48:51], v[140:143], v[180:183], v[48:51]
	v_mfma_f32_16x16x32_bf16 v[44:47], v[132:135], v[188:191], v[44:47]
	v_mfma_f32_16x16x32_bf16 v[40:43], v[140:143], v[188:191], v[40:43]
	v_mfma_f32_16x16x32_bf16 v[36:39], v[132:135], v[196:199], v[36:39]
	v_mfma_f32_16x16x32_bf16 v[32:35], v[140:143], v[196:199], v[32:35]
	v_mfma_f32_16x16x32_bf16 v[28:31], v[144:147], v[168:171], v[28:31]
	v_mfma_f32_16x16x32_bf16 v[24:27], v[152:155], v[168:171], v[24:27]
	v_mfma_f32_16x16x32_bf16 v[20:23], v[144:147], v[176:179], v[20:23]
	v_mfma_f32_16x16x32_bf16 v[16:19], v[152:155], v[176:179], v[16:19]
	v_mfma_f32_16x16x32_bf16 v[12:15], v[144:147], v[184:187], v[12:15]
	v_mfma_f32_16x16x32_bf16 v[8:11], v[152:155], v[184:187], v[8:11]
	v_mfma_f32_16x16x32_bf16 v[4:7], v[144:147], v[192:195], v[4:7]
	v_mfma_f32_16x16x32_bf16 v[0:3], v[152:155], v[192:195], v[0:3]
	v_mfma_f32_16x16x32_bf16 v[28:31], v[148:151], v[172:175], v[28:31]
	v_mfma_f32_16x16x32_bf16 v[24:27], v[156:159], v[172:175], v[24:27]
	v_mfma_f32_16x16x32_bf16 v[20:23], v[148:151], v[180:183], v[20:23]
	v_mfma_f32_16x16x32_bf16 v[16:19], v[156:159], v[180:183], v[16:19]
	v_mfma_f32_16x16x32_bf16 v[12:15], v[148:151], v[188:191], v[12:15]
	v_mfma_f32_16x16x32_bf16 v[8:11], v[156:159], v[188:191], v[8:11]
	v_mfma_f32_16x16x32_bf16 v[4:7], v[148:151], v[196:199], v[4:7]
	v_mfma_f32_16x16x32_bf16 v[0:3], v[156:159], v[196:199], v[0:3]
	s_barrier
	s_add_i32 s65, 0, 0x18000
	s_add_i32 s57, 0, 0x1c000
	v_add_u32_e32 v204, s65, v206
	v_add_u32_e32 v205, s57, v206
	ds_read_b128 v[128:131], v204
	ds_read_b128 v[132:135], v204 offset:1024
	ds_read_b128 v[136:139], v204 offset:2048
	ds_read_b128 v[140:143], v204 offset:3072
	ds_read_b128 v[144:147], v205
	ds_read_b128 v[148:151], v205 offset:1024
	ds_read_b128 v[152:155], v205 offset:2048
	ds_read_b128 v[156:159], v205 offset:3072
	s_add_u32 s74, s18, 0x14000
	s_addc_u32 s75, s19, 0
	s_mov_b32 m0, s39
	ds_read_b128 v[168:171], v207 offset:32768
	ds_read_b128 v[172:175], v207 offset:33792
	ds_read_b128 v[176:179], v207 offset:34816
	ds_read_b128 v[180:183], v207 offset:35840
	ds_read_b128 v[184:187], v207 offset:36864
	ds_read_b128 v[188:191], v207 offset:37888
	ds_read_b128 v[192:195], v207 offset:38912
	ds_read_b128 v[196:199], v207 offset:39936
	global_load_lds_dwordx4 v160, s[74:75]
	s_mov_b32 m0, s41
	s_nop 0
	global_load_lds_dwordx4 v164, s[74:75]
	s_waitcnt vmcnt(8)
	s_waitcnt lgkmcnt(0)
	s_barrier
	s_waitcnt lgkmcnt(0)
	v_mfma_f32_16x16x32_bf16 v[124:127], v[128:131], v[168:171], v[124:127]
	v_mfma_f32_16x16x32_bf16 v[120:123], v[136:139], v[168:171], v[120:123]
	v_mfma_f32_16x16x32_bf16 v[116:119], v[128:131], v[176:179], v[116:119]
	v_mfma_f32_16x16x32_bf16 v[112:115], v[136:139], v[176:179], v[112:115]
	v_mfma_f32_16x16x32_bf16 v[108:111], v[128:131], v[184:187], v[108:111]
	v_mfma_f32_16x16x32_bf16 v[104:107], v[136:139], v[184:187], v[104:107]
	v_mfma_f32_16x16x32_bf16 v[100:103], v[128:131], v[192:195], v[100:103]
	v_mfma_f32_16x16x32_bf16 v[96:99], v[136:139], v[192:195], v[96:99]
	v_mfma_f32_16x16x32_bf16 v[124:127], v[132:135], v[172:175], v[124:127]
	v_mfma_f32_16x16x32_bf16 v[120:123], v[140:143], v[172:175], v[120:123]
	v_mfma_f32_16x16x32_bf16 v[116:119], v[132:135], v[180:183], v[116:119]
	v_mfma_f32_16x16x32_bf16 v[112:115], v[140:143], v[180:183], v[112:115]
	v_mfma_f32_16x16x32_bf16 v[108:111], v[132:135], v[188:191], v[108:111]
	v_mfma_f32_16x16x32_bf16 v[104:107], v[140:143], v[188:191], v[104:107]
	v_mfma_f32_16x16x32_bf16 v[100:103], v[132:135], v[196:199], v[100:103]
	v_mfma_f32_16x16x32_bf16 v[96:99], v[140:143], v[196:199], v[96:99]
	v_mfma_f32_16x16x32_bf16 v[92:95], v[144:147], v[168:171], v[92:95]
	v_mfma_f32_16x16x32_bf16 v[88:91], v[152:155], v[168:171], v[88:91]
	v_mfma_f32_16x16x32_bf16 v[84:87], v[144:147], v[176:179], v[84:87]
	v_mfma_f32_16x16x32_bf16 v[80:83], v[152:155], v[176:179], v[80:83]
	v_mfma_f32_16x16x32_bf16 v[76:79], v[144:147], v[184:187], v[76:79]
	v_mfma_f32_16x16x32_bf16 v[72:75], v[152:155], v[184:187], v[72:75]
	v_mfma_f32_16x16x32_bf16 v[68:71], v[144:147], v[192:195], v[68:71]
	v_mfma_f32_16x16x32_bf16 v[64:67], v[152:155], v[192:195], v[64:67]
	v_mfma_f32_16x16x32_bf16 v[92:95], v[148:151], v[172:175], v[92:95]
	v_mfma_f32_16x16x32_bf16 v[88:91], v[156:159], v[172:175], v[88:91]
	v_mfma_f32_16x16x32_bf16 v[84:87], v[148:151], v[180:183], v[84:87]
	v_mfma_f32_16x16x32_bf16 v[80:83], v[156:159], v[180:183], v[80:83]
	v_mfma_f32_16x16x32_bf16 v[76:79], v[148:151], v[188:191], v[76:79]
	v_mfma_f32_16x16x32_bf16 v[72:75], v[156:159], v[188:191], v[72:75]
	v_mfma_f32_16x16x32_bf16 v[68:71], v[148:151], v[196:199], v[68:71]
	v_mfma_f32_16x16x32_bf16 v[64:67], v[156:159], v[196:199], v[64:67]
	s_barrier
; #define PG8_STAGE(bufoff, gbase, voff) do { _Pragma("unroll") for (int _i = 0; _i < 2; ++_i) \
;         __builtin_amdgcn_global_load_lds((const unsigned*)((const char*)(gbase) + (voff)[_i]), (PG8_LAS unsigned*)(lds + (bufoff) + ldsw + _i * 8192), 16, 0, 0); } while (0)
; #define PG8_LDA(dst, b, h) do { _Pragma("unroll") for (int m = 0; m < 4; ++m) _Pragma("unroll") for (int k = 0; k < 2; ++k) dst[m][k] = *(const PG8_LAS bf16x8*)(lds + PG8_SA(b, h) + aoff + m * 2048 + k * 1024); } while (0)
; #define PG8_LDB(dst, b, h) do { _Pragma("unroll") for (int n = 0; n < 2; ++n) _Pragma("unroll") for (int k = 0; k < 2; ++k) dst[n][k] = *(const PG8_LAS bf16x8*)(lds + PG8_SB(b, h) + boff + n * 2048 + k * 1024); } while (0)
; #define PG8_MMA(ai, bj, At, Bt) do { __builtin_amdgcn_s_setprio(1); _Pragma("unroll") for (int m = 0; m < 4; ++m) _Pragma("unroll") for (int n = 0; n < 2; ++n) _Pragma("unroll") for (int k = 0; k < 2; ++k) \
;         acc[ai][bj][m][n] = __builtin_amdgcn_mfma_f32_16x16x32_bf16(Bt[n][k], At[m][k], acc[ai][bj][m][n], 0, 0, 0); __builtin_amdgcn_s_setprio(0); } while (0)
; #define PG8_WAIT_V(n) asm volatile("s_waitcnt vmcnt(" #n ")" ::: "memory")
; template <class Epi, class Sched, bool ALIGN_EPI = false, bool SP2 = false>
; __device__ __forceinline__ void gemm_phase(PG8_LAS unsigned char* lds, const Gemm g, const Sched& S, const Epi& E) {
;     ...
;             PG8_LDB(B0, 0, 0); PG8_LDB(B1, 0, 1); PG8_SCHED; PG8_LDA(At, 0, 0); PG8_STAGE(PG8_SA(1, 1), a1 + hstep, voffA);
;             PG8_WAIT_V(8); PG8_WAIT_L(0); PG8_BAR; PG8_MMA(0, 0, At, B0); PG8_MMA(0, 1, At, B1); PG8_BAR; PG8_SCHED;
;             PG8_LDA(At, 0, 1); PG8_STAGE(PG8_SB(0, 0), b2, voffB); PG8_STAGE(PG8_SB(0, 1), b2 + hstep, voffB); PG8_STAGE(PG8_SA(0, 0), a2, voffA);
;             PG8_WAIT_V(8); PG8_WAIT_L(0); PG8_BAR; PG8_MMA(1, 0, At, B0); PG8_MMA(1, 1, At, B1); PG8_BAR; PG8_SCHED;
;             PG8_LDB(B0, 1, 0); PG8_LDB(B1, 1, 1); PG8_SCHED; PG8_LDA(At, 1, 0); PG8_STAGE(PG8_SA(0, 1), a2 + hstep, voffA);
;             PG8_WAIT_V(8); PG8_WAIT_L(0); PG8_BAR; PG8_MMA(0, 0, At, B0); PG8_MMA(0, 1, At, B1); PG8_BAR; PG8_SCHED;
;             PG8_LDA(At, 1, 1); PG8_STAGE(PG8_SB(1, 0), b3, voffB); PG8_STAGE(PG8_SB(1, 1), b3 + hstep, voffB); PG8_STAGE(PG8_SA(1, 0), a3, voffA);
;             PG8_WAIT_V(8); PG8_WAIT_L(0); PG8_BAR; PG8_MMA(1, 0, At, B0); PG8_MMA(1, 1, At, B1); PG8_BAR; PG8_SCHED;
	s_add_u32 s74, s66, 0x18000
	s_addc_u32 s75, s67, 0
	s_add_i32 s65, s65, s30
	s_add_i32 s40, s65, 0x2000
	s_mov_b32 m0, s65
	s_add_u32 s66, s66, 0x1c000
	ds_read_b128 v[168:171], v207 offset:49152
	ds_read_b128 v[172:175], v207 offset:50176
	ds_read_b128 v[176:179], v207 offset:51200
	ds_read_b128 v[180:183], v207 offset:52224
	ds_read_b128 v[184:187], v207 offset:53248
	ds_read_b128 v[188:191], v207 offset:54272
	ds_read_b128 v[192:195], v207 offset:55296
	ds_read_b128 v[196:199], v207 offset:56320
	global_load_lds_dwordx4 v162, s[74:75]
	s_mov_b32 m0, s40
	s_addc_u32 s67, s67, 0
	s_add_i32 s57, s57, s30
	global_load_lds_dwordx4 v166, s[74:75]
	s_mov_b32 m0, s57
	s_add_i32 s61, s57, 0x2000
	global_load_lds_dwordx4 v162, s[66:67]
	s_mov_b32 m0, s61
	s_nop 0
	global_load_lds_dwordx4 v166, s[66:67]
	s_mov_b32 m0, s51
	s_nop 0
	global_load_lds_dwordx4 v160, s[72:73]
	s_mov_b32 m0, s52
	s_nop 0
	global_load_lds_dwordx4 v164, s[72:73]
	s_waitcnt vmcnt(8)
	s_waitcnt lgkmcnt(0)
	s_barrier
	s_waitcnt lgkmcnt(0)
	v_mfma_f32_16x16x32_bf16 v[60:63], v[128:131], v[168:171], v[60:63]
	v_mfma_f32_16x16x32_bf16 v[56:59], v[136:139], v[168:171], v[56:59]
	v_mfma_f32_16x16x32_bf16 v[52:55], v[128:131], v[176:179], v[52:55]
	v_mfma_f32_16x16x32_bf16 v[48:51], v[136:139], v[176:179], v[48:51]
	v_mfma_f32_16x16x32_bf16 v[44:47], v[128:131], v[184:187], v[44:47]
	v_mfma_f32_16x16x32_bf16 v[40:43], v[136:139], v[184:187], v[40:43]
	v_mfma_f32_16x16x32_bf16 v[36:39], v[128:131], v[192:195], v[36:39]
	v_mfma_f32_16x16x32_bf16 v[32:35], v[136:139], v[192:195], v[32:35]
	v_mfma_f32_16x16x32_bf16 v[60:63], v[132:135], v[172:175], v[60:63]
	v_mfma_f32_16x16x32_bf16 v[56:59], v[140:143], v[172:175], v[56:59]
	v_mfma_f32_16x16x32_bf16 v[52:55], v[132:135], v[180:183], v[52:55]
	v_mfma_f32_16x16x32_bf16 v[48:51], v[140:143], v[180:183], v[48:51]
	v_mfma_f32_16x16x32_bf16 v[44:47], v[132:135], v[188:191], v[44:47]
	v_mfma_f32_16x16x32_bf16 v[40:43], v[140:143], v[188:191], v[40:43]
	v_mfma_f32_16x16x32_bf16 v[36:39], v[132:135], v[196:199], v[36:39]
	v_mfma_f32_16x16x32_bf16 v[32:35], v[140:143], v[196:199], v[32:35]
	v_mfma_f32_16x16x32_bf16 v[28:31], v[144:147], v[168:171], v[28:31]
	v_mfma_f32_16x16x32_bf16 v[24:27], v[152:155], v[168:171], v[24:27]
	v_mfma_f32_16x16x32_bf16 v[20:23], v[144:147], v[176:179], v[20:23]
	v_mfma_f32_16x16x32_bf16 v[16:19], v[152:155], v[176:179], v[16:19]
	v_mfma_f32_16x16x32_bf16 v[12:15], v[144:147], v[184:187], v[12:15]
	v_mfma_f32_16x16x32_bf16 v[8:11], v[152:155], v[184:187], v[8:11]
	v_mfma_f32_16x16x32_bf16 v[4:7], v[144:147], v[192:195], v[4:7]
	v_mfma_f32_16x16x32_bf16 v[0:3], v[152:155], v[192:195], v[0:3]
	v_mfma_f32_16x16x32_bf16 v[28:31], v[148:151], v[172:175], v[28:31]
	v_mfma_f32_16x16x32_bf16 v[24:27], v[156:159], v[172:175], v[24:27]
	v_mfma_f32_16x16x32_bf16 v[20:23], v[148:151], v[180:183], v[20:23]
	v_mfma_f32_16x16x32_bf16 v[16:19], v[156:159], v[180:183], v[16:19]
	v_mfma_f32_16x16x32_bf16 v[12:15], v[148:151], v[188:191], v[12:15]
	v_mfma_f32_16x16x32_bf16 v[8:11], v[156:159], v[188:191], v[8:11]
	v_mfma_f32_16x16x32_bf16 v[4:7], v[148:151], v[196:199], v[4:7]
	v_mfma_f32_16x16x32_bf16 v[0:3], v[156:159], v[196:199], v[0:3]
	s_barrier
	ds_read_b128 v[128:131], v202
	ds_read_b128 v[132:135], v202 offset:1024
	ds_read_b128 v[136:139], v202 offset:2048
	ds_read_b128 v[140:143], v202 offset:3072
	ds_read_b128 v[144:147], v203
	ds_read_b128 v[148:151], v203 offset:1024
	ds_read_b128 v[152:155], v203 offset:2048
	ds_read_b128 v[156:159], v203 offset:3072
	s_add_u32 s66, s70, 0x8000
	s_addc_u32 s67, s71, 0
	s_add_u32 s18, s18, 0x1c000
	s_addc_u32 s19, s19, 0
	s_mov_b32 m0, s64
	ds_read_b128 v[168:171], v207
	ds_read_b128 v[172:175], v207 offset:1024
	ds_read_b128 v[176:179], v207 offset:2048
	ds_read_b128 v[180:183], v207 offset:3072
	ds_read_b128 v[184:187], v207 offset:4096
	ds_read_b128 v[188:191], v207 offset:5120
	ds_read_b128 v[192:195], v207 offset:6144
	ds_read_b128 v[196:199], v207 offset:7168
	global_load_lds_dwordx4 v160, s[18:19]
	s_mov_b32 m0, s5
	s_nop 0
	global_load_lds_dwordx4 v164, s[18:19]
	s_waitcnt vmcnt(8)
	s_waitcnt lgkmcnt(0)
	s_barrier
	s_waitcnt lgkmcnt(0)
	v_mfma_f32_16x16x32_bf16 v[124:127], v[128:131], v[168:171], v[124:127]
	v_mfma_f32_16x16x32_bf16 v[120:123], v[136:139], v[168:171], v[120:123]
	v_mfma_f32_16x16x32_bf16 v[116:119], v[128:131], v[176:179], v[116:119]
	v_mfma_f32_16x16x32_bf16 v[112:115], v[136:139], v[176:179], v[112:115]
	v_mfma_f32_16x16x32_bf16 v[108:111], v[128:131], v[184:187], v[108:111]
	v_mfma_f32_16x16x32_bf16 v[104:107], v[136:139], v[184:187], v[104:107]
	v_mfma_f32_16x16x32_bf16 v[100:103], v[128:131], v[192:195], v[100:103]
	v_mfma_f32_16x16x32_bf16 v[96:99], v[136:139], v[192:195], v[96:99]
	v_mfma_f32_16x16x32_bf16 v[124:127], v[132:135], v[172:175], v[124:127]
	v_mfma_f32_16x16x32_bf16 v[120:123], v[140:143], v[172:175], v[120:123]
	v_mfma_f32_16x16x32_bf16 v[116:119], v[132:135], v[180:183], v[116:119]
	v_mfma_f32_16x16x32_bf16 v[112:115], v[140:143], v[180:183], v[112:115]
	v_mfma_f32_16x16x32_bf16 v[108:111], v[132:135], v[188:191], v[108:111]
	v_mfma_f32_16x16x32_bf16 v[104:107], v[140:143], v[188:191], v[104:107]
	v_mfma_f32_16x16x32_bf16 v[100:103], v[132:135], v[196:199], v[100:103]
	v_mfma_f32_16x16x32_bf16 v[96:99], v[140:143], v[196:199], v[96:99]
	v_mfma_f32_16x16x32_bf16 v[92:95], v[144:147], v[168:171], v[92:95]
	v_mfma_f32_16x16x32_bf16 v[88:91], v[152:155], v[168:171], v[88:91]
	v_mfma_f32_16x16x32_bf16 v[84:87], v[144:147], v[176:179], v[84:87]
	v_mfma_f32_16x16x32_bf16 v[80:83], v[152:155], v[176:179], v[80:83]
	v_mfma_f32_16x16x32_bf16 v[76:79], v[144:147], v[184:187], v[76:79]
	v_mfma_f32_16x16x32_bf16 v[72:75], v[152:155], v[184:187], v[72:75]
	v_mfma_f32_16x16x32_bf16 v[68:71], v[144:147], v[192:195], v[68:71]
	v_mfma_f32_16x16x32_bf16 v[64:67], v[152:155], v[192:195], v[64:67]
	v_mfma_f32_16x16x32_bf16 v[92:95], v[148:151], v[172:175], v[92:95]
	v_mfma_f32_16x16x32_bf16 v[88:91], v[156:159], v[172:175], v[88:91]
	v_mfma_f32_16x16x32_bf16 v[84:87], v[148:151], v[180:183], v[84:87]
	v_mfma_f32_16x16x32_bf16 v[80:83], v[156:159], v[180:183], v[80:83]
	v_mfma_f32_16x16x32_bf16 v[76:79], v[148:151], v[188:191], v[76:79]
	v_mfma_f32_16x16x32_bf16 v[72:75], v[156:159], v[188:191], v[72:75]
	v_mfma_f32_16x16x32_bf16 v[68:71], v[148:151], v[196:199], v[68:71]
	v_mfma_f32_16x16x32_bf16 v[64:67], v[156:159], v[196:199], v[64:67]
	s_barrier
; #define PG8_STAGE(bufoff, gbase, voff) do { _Pragma("unroll") for (int _i = 0; _i < 2; ++_i) \
;         __builtin_amdgcn_global_load_lds((const unsigned*)((const char*)(gbase) + (voff)[_i]), (PG8_LAS unsigned*)(lds + (bufoff) + ldsw + _i * 8192), 16, 0, 0); } while (0)
; #define PG8_LDA(dst, b, h) do { _Pragma("unroll") for (int m = 0; m < 4; ++m) _Pragma("unroll") for (int k = 0; k < 2; ++k) dst[m][k] = *(const PG8_LAS bf16x8*)(lds + PG8_SA(b, h) + aoff + m * 2048 + k * 1024); } while (0)
; #define PG8_LDB(dst, b, h) do { _Pragma("unroll") for (int n = 0; n < 2; ++n) _Pragma("unroll") for (int k = 0; k < 2; ++k) dst[n][k] = *(const PG8_LAS bf16x8*)(lds + PG8_SB(b, h) + boff + n * 2048 + k * 1024); } while (0)
; #define PG8_MMA(ai, bj, At, Bt) do { __builtin_amdgcn_s_setprio(1); _Pragma("unroll") for (int m = 0; m < 4; ++m) _Pragma("unroll") for (int n = 0; n < 2; ++n) _Pragma("unroll") for (int k = 0; k < 2; ++k) \
;         acc[ai][bj][m][n] = __builtin_amdgcn_mfma_f32_16x16x32_bf16(Bt[n][k], At[m][k], acc[ai][bj][m][n], 0, 0, 0); __builtin_amdgcn_s_setprio(0); } while (0)
; #define PG8_WAIT_V(n) asm volatile("s_waitcnt vmcnt(" #n ")" ::: "memory")
; template <class Epi, class Sched, bool ALIGN_EPI = false, bool SP2 = false>
; __device__ __forceinline__ void gemm_phase(PG8_LAS unsigned char* lds, const Gemm g, const Sched& S, const Epi& E) {
;     ...
;             PG8_LDB(B0, 0, 0); PG8_LDB(B1, 0, 1); PG8_SCHED; PG8_LDA(At, 0, 0); PG8_STAGE(PG8_SA(1, 1), a1 + hstep, voffA);
;             PG8_WAIT_V(8); PG8_WAIT_L(0); PG8_BAR; PG8_MMA(0, 0, At, B0); PG8_MMA(0, 1, At, B1); PG8_BAR; PG8_SCHED;
;             PG8_LDA(At, 0, 1); PG8_STAGE(PG8_SB(0, 0), b2, voffB); PG8_STAGE(PG8_SB(0, 1), b2 + hstep, voffB); PG8_STAGE(PG8_SA(0, 0), a2, voffA);
;             PG8_WAIT_V(8); PG8_WAIT_L(0); PG8_BAR; PG8_MMA(1, 0, At, B0); PG8_MMA(1, 1, At, B1); PG8_BAR; PG8_SCHED;
;             PG8_LDB(B0, 1, 0); PG8_LDB(B1, 1, 1); PG8_SCHED; PG8_LDA(At, 1, 0); PG8_STAGE(PG8_SA(0, 1), a2 + hstep, voffA);
;             PG8_WAIT_V(8); PG8_WAIT_L(0); PG8_BAR; PG8_MMA(0, 0, At, B0); PG8_MMA(0, 1, At, B1); PG8_BAR; PG8_SCHED;
;             PG8_LDA(At, 1, 1); PG8_STAGE(PG8_SB(1, 0), b3, voffB); PG8_STAGE(PG8_SB(1, 1), b3 + hstep, voffB); PG8_STAGE(PG8_SA(1, 0), a3, voffA);
;             PG8_WAIT_V(8); PG8_WAIT_L(0); PG8_BAR; PG8_MMA(1, 0, At, B0); PG8_MMA(1, 1, At, B1); PG8_BAR; PG8_SCHED;
	s_mov_b32 m0, s59
	s_add_u32 s18, s68, 0x4000
	ds_read_b128 v[168:171], v207 offset:16384
	ds_read_b128 v[172:175], v207 offset:17408
	ds_read_b128 v[176:179], v207 offset:18432
	ds_read_b128 v[180:183], v207 offset:19456
	ds_read_b128 v[184:187], v207 offset:20480
	ds_read_b128 v[188:191], v207 offset:21504
	ds_read_b128 v[192:195], v207 offset:22528
	ds_read_b128 v[196:199], v207 offset:23552
	global_load_lds_dwordx4 v162, s[68:69]
	s_mov_b32 m0, s11
	s_addc_u32 s19, s69, 0
	global_load_lds_dwordx4 v166, s[68:69]
	s_mov_b32 m0, s13
	s_nop 0
	global_load_lds_dwordx4 v162, s[18:19]
	s_mov_b32 m0, s21
	s_nop 0
	global_load_lds_dwordx4 v166, s[18:19]
	s_mov_b32 m0, s33
	s_nop 0
	global_load_lds_dwordx4 v160, s[70:71]
	s_mov_b32 m0, s37
	s_nop 0
	global_load_lds_dwordx4 v164, s[70:71]
	s_waitcnt vmcnt(8)
	s_waitcnt lgkmcnt(0)
	s_barrier
	s_waitcnt lgkmcnt(0)
	v_mfma_f32_16x16x32_bf16 v[60:63], v[128:131], v[168:171], v[60:63]
	v_mfma_f32_16x16x32_bf16 v[56:59], v[136:139], v[168:171], v[56:59]
	v_mfma_f32_16x16x32_bf16 v[52:55], v[128:131], v[176:179], v[52:55]
	v_mfma_f32_16x16x32_bf16 v[48:51], v[136:139], v[176:179], v[48:51]
	v_mfma_f32_16x16x32_bf16 v[44:47], v[128:131], v[184:187], v[44:47]
	v_mfma_f32_16x16x32_bf16 v[40:43], v[136:139], v[184:187], v[40:43]
	v_mfma_f32_16x16x32_bf16 v[36:39], v[128:131], v[192:195], v[36:39]
	v_mfma_f32_16x16x32_bf16 v[32:35], v[136:139], v[192:195], v[32:35]
	v_mfma_f32_16x16x32_bf16 v[60:63], v[132:135], v[172:175], v[60:63]
	v_mfma_f32_16x16x32_bf16 v[56:59], v[140:143], v[172:175], v[56:59]
	v_mfma_f32_16x16x32_bf16 v[52:55], v[132:135], v[180:183], v[52:55]
	v_mfma_f32_16x16x32_bf16 v[48:51], v[140:143], v[180:183], v[48:51]
	v_mfma_f32_16x16x32_bf16 v[44:47], v[132:135], v[188:191], v[44:47]
	v_mfma_f32_16x16x32_bf16 v[40:43], v[140:143], v[188:191], v[40:43]
	v_mfma_f32_16x16x32_bf16 v[36:39], v[132:135], v[196:199], v[36:39]
	v_mfma_f32_16x16x32_bf16 v[32:35], v[140:143], v[196:199], v[32:35]
	v_mfma_f32_16x16x32_bf16 v[28:31], v[144:147], v[168:171], v[28:31]
	v_mfma_f32_16x16x32_bf16 v[24:27], v[152:155], v[168:171], v[24:27]
	v_mfma_f32_16x16x32_bf16 v[20:23], v[144:147], v[176:179], v[20:23]
	v_mfma_f32_16x16x32_bf16 v[16:19], v[152:155], v[176:179], v[16:19]
	v_mfma_f32_16x16x32_bf16 v[12:15], v[144:147], v[184:187], v[12:15]
	v_mfma_f32_16x16x32_bf16 v[8:11], v[152:155], v[184:187], v[8:11]
	v_mfma_f32_16x16x32_bf16 v[4:7], v[144:147], v[192:195], v[4:7]
	v_mfma_f32_16x16x32_bf16 v[0:3], v[152:155], v[192:195], v[0:3]
	v_mfma_f32_16x16x32_bf16 v[28:31], v[148:151], v[172:175], v[28:31]
	v_mfma_f32_16x16x32_bf16 v[24:27], v[156:159], v[172:175], v[24:27]
	v_mfma_f32_16x16x32_bf16 v[20:23], v[148:151], v[180:183], v[20:23]
	v_mfma_f32_16x16x32_bf16 v[16:19], v[156:159], v[180:183], v[16:19]
	v_mfma_f32_16x16x32_bf16 v[12:15], v[148:151], v[188:191], v[12:15]
	v_mfma_f32_16x16x32_bf16 v[8:11], v[156:159], v[188:191], v[8:11]
	v_mfma_f32_16x16x32_bf16 v[4:7], v[148:151], v[196:199], v[4:7]
	v_mfma_f32_16x16x32_bf16 v[0:3], v[156:159], v[196:199], v[0:3]
	s_barrier
	ds_read_b128 v[128:131], v204
	ds_read_b128 v[132:135], v204 offset:1024
	ds_read_b128 v[136:139], v204 offset:2048
	ds_read_b128 v[140:143], v204 offset:3072
	ds_read_b128 v[144:147], v205
	ds_read_b128 v[148:151], v205 offset:1024
	ds_read_b128 v[152:155], v205 offset:2048
	ds_read_b128 v[156:159], v205 offset:3072
	s_add_u32 s18, s70, 0x4000
	s_addc_u32 s19, s71, 0
	s_mov_b32 m0, s39
	ds_read_b128 v[168:171], v207 offset:32768
	ds_read_b128 v[172:175], v207 offset:33792
	ds_read_b128 v[176:179], v207 offset:34816
	ds_read_b128 v[180:183], v207 offset:35840
	ds_read_b128 v[184:187], v207 offset:36864
	ds_read_b128 v[188:191], v207 offset:37888
	ds_read_b128 v[192:195], v207 offset:38912
	ds_read_b128 v[196:199], v207 offset:39936
	global_load_lds_dwordx4 v160, s[18:19]
	s_mov_b32 m0, s41
	s_nop 0
	global_load_lds_dwordx4 v164, s[18:19]
	s_waitcnt vmcnt(8)
	s_waitcnt lgkmcnt(0)
	s_barrier
; #define PG8_STAGE(bufoff, gbase, voff) do { _Pragma("unroll") for (int _i = 0; _i < 2; ++_i) \
;         __builtin_amdgcn_global_load_lds((const unsigned*)((const char*)(gbase) + (voff)[_i]), (PG8_LAS unsigned*)(lds + (bufoff) + ldsw + _i * 8192), 16, 0, 0); } while (0)
; #define PG8_LDA(dst, b, h) do { _Pragma("unroll") for (int m = 0; m < 4; ++m) _Pragma("unroll") for (int k = 0; k < 2; ++k) dst[m][k] = *(const PG8_LAS bf16x8*)(lds + PG8_SA(b, h) + aoff + m * 2048 + k * 1024); } while (0)
; #define PG8_LDB(dst, b, h) do { _Pragma("unroll") for (int n = 0; n < 2; ++n) _Pragma("unroll") for (int k = 0; k < 2; ++k) dst[n][k] = *(const PG8_LAS bf16x8*)(lds + PG8_SB(b, h) + boff + n * 2048 + k * 1024); } while (0)
; #define PG8_MMA(ai, bj, At, Bt) do { __builtin_amdgcn_s_setprio(1); _Pragma("unroll") for (int m = 0; m < 4; ++m) _Pragma("unroll") for (int n = 0; n < 2; ++n) _Pragma("unroll") for (int k = 0; k < 2; ++k) \
;         acc[ai][bj][m][n] = __builtin_amdgcn_mfma_f32_16x16x32_bf16(Bt[n][k], At[m][k], acc[ai][bj][m][n], 0, 0, 0); __builtin_amdgcn_s_setprio(0); } while (0)
; #define PG8_WAIT_V(n) asm volatile("s_waitcnt vmcnt(" #n ")" ::: "memory")
; #define PG8_WAIT_L(n) asm volatile("s_waitcnt lgkmcnt(" #n ")" ::: "memory")
; #define PG8_BAR __builtin_amdgcn_s_barrier()
; #define PG8_SCHED __builtin_amdgcn_sched_barrier(0)
; template <class Epi, class Sched, bool ALIGN_EPI = false, bool SP2 = false>
; __device__ __forceinline__ void gemm_phase(PG8_LAS unsigned char* lds, const Gemm g, const Sched& S, const Epi& E) {
;     ...
;             PG8_LDB(B0, 1, 0); PG8_LDB(B1, 1, 1); PG8_SCHED; PG8_LDA(At, 1, 0); PG8_STAGE(PG8_SA(0, 1), a2 + hstep, voffA);
;             PG8_WAIT_V(8); PG8_WAIT_L(0); PG8_BAR; PG8_MMA(0, 0, At, B0); PG8_MMA(0, 1, At, B1); PG8_BAR; PG8_SCHED;
;             PG8_LDA(At, 1, 1); PG8_STAGE(PG8_SB(1, 0), b3, voffB); PG8_STAGE(PG8_SB(1, 1), b3 + hstep, voffB); PG8_STAGE(PG8_SA(1, 0), a3, voffA);
;             PG8_WAIT_V(8); PG8_WAIT_L(0); PG8_BAR; PG8_MMA(1, 0, At, B0); PG8_MMA(1, 1, At, B1); PG8_BAR; PG8_SCHED;
;     ...
;         if constexpr (ALIGN_EPI) { if (wr == 0) PG8_BAR; }
	s_waitcnt lgkmcnt(0)
	v_mfma_f32_16x16x32_bf16 v[124:127], v[128:131], v[168:171], v[124:127]
	v_mfma_f32_16x16x32_bf16 v[120:123], v[136:139], v[168:171], v[120:123]
	v_mfma_f32_16x16x32_bf16 v[116:119], v[128:131], v[176:179], v[116:119]
	v_mfma_f32_16x16x32_bf16 v[112:115], v[136:139], v[176:179], v[112:115]
	v_mfma_f32_16x16x32_bf16 v[108:111], v[128:131], v[184:187], v[108:111]
	v_mfma_f32_16x16x32_bf16 v[104:107], v[136:139], v[184:187], v[104:107]
	v_mfma_f32_16x16x32_bf16 v[100:103], v[128:131], v[192:195], v[100:103]
	v_mfma_f32_16x16x32_bf16 v[96:99], v[136:139], v[192:195], v[96:99]
	v_mfma_f32_16x16x32_bf16 v[124:127], v[132:135], v[172:175], v[124:127]
	v_mfma_f32_16x16x32_bf16 v[120:123], v[140:143], v[172:175], v[120:123]
	v_mfma_f32_16x16x32_bf16 v[116:119], v[132:135], v[180:183], v[116:119]
	v_mfma_f32_16x16x32_bf16 v[112:115], v[140:143], v[180:183], v[112:115]
	v_mfma_f32_16x16x32_bf16 v[108:111], v[132:135], v[188:191], v[108:111]
	v_mfma_f32_16x16x32_bf16 v[104:107], v[140:143], v[188:191], v[104:107]
	v_mfma_f32_16x16x32_bf16 v[100:103], v[132:135], v[196:199], v[100:103]
	v_mfma_f32_16x16x32_bf16 v[96:99], v[140:143], v[196:199], v[96:99]
	v_mfma_f32_16x16x32_bf16 v[92:95], v[144:147], v[168:171], v[92:95]
	v_mfma_f32_16x16x32_bf16 v[88:91], v[152:155], v[168:171], v[88:91]
	v_mfma_f32_16x16x32_bf16 v[84:87], v[144:147], v[176:179], v[84:87]
	v_mfma_f32_16x16x32_bf16 v[80:83], v[152:155], v[176:179], v[80:83]
	v_mfma_f32_16x16x32_bf16 v[76:79], v[144:147], v[184:187], v[76:79]
	v_mfma_f32_16x16x32_bf16 v[72:75], v[152:155], v[184:187], v[72:75]
	v_mfma_f32_16x16x32_bf16 v[68:71], v[144:147], v[192:195], v[68:71]
	v_mfma_f32_16x16x32_bf16 v[64:67], v[152:155], v[192:195], v[64:67]
	v_mfma_f32_16x16x32_bf16 v[92:95], v[148:151], v[172:175], v[92:95]
	v_mfma_f32_16x16x32_bf16 v[88:91], v[156:159], v[172:175], v[88:91]
	v_mfma_f32_16x16x32_bf16 v[84:87], v[148:151], v[180:183], v[84:87]
	v_mfma_f32_16x16x32_bf16 v[80:83], v[156:159], v[180:183], v[80:83]
	v_mfma_f32_16x16x32_bf16 v[76:79], v[148:151], v[188:191], v[76:79]
	v_mfma_f32_16x16x32_bf16 v[72:75], v[156:159], v[188:191], v[72:75]
	v_mfma_f32_16x16x32_bf16 v[68:71], v[148:151], v[196:199], v[68:71]
	v_mfma_f32_16x16x32_bf16 v[64:67], v[156:159], v[196:199], v[64:67]
	s_barrier
	s_add_u32 s18, s68, 0x8000
	s_addc_u32 s19, s69, 0
	s_mov_b32 m0, s65
	ds_read_b128 v[168:171], v207 offset:49152
	ds_read_b128 v[172:175], v207 offset:50176
	ds_read_b128 v[176:179], v207 offset:51200
	ds_read_b128 v[180:183], v207 offset:52224
	ds_read_b128 v[184:187], v207 offset:53248
	ds_read_b128 v[188:191], v207 offset:54272
	ds_read_b128 v[192:195], v207 offset:55296
	ds_read_b128 v[196:199], v207 offset:56320
	global_load_lds_dwordx4 v162, s[18:19]
	v_lshl_add_u64 v[200:201], s[18:19], 0, v[166:167]
	s_add_u32 s18, s68, 0xc000
	s_mov_b32 m0, s40
	s_addc_u32 s19, s69, 0
	global_load_lds_dwordx4 v[200:201], off
	s_mov_b32 m0, s57
	s_nop 0
	global_load_lds_dwordx4 v162, s[18:19]
	s_mov_b32 m0, s61
	s_nop 0
	global_load_lds_dwordx4 v166, s[18:19]
	s_mov_b32 m0, s51
	s_nop 0
	global_load_lds_dwordx4 v160, s[66:67]
	s_mov_b32 m0, s52
	s_nop 0
	global_load_lds_dwordx4 v164, s[66:67]
	s_waitcnt vmcnt(8)
	s_waitcnt lgkmcnt(0)
	s_barrier
	s_waitcnt lgkmcnt(0)
	v_mfma_f32_16x16x32_bf16 v[60:63], v[128:131], v[168:171], v[60:63]
	v_mfma_f32_16x16x32_bf16 v[56:59], v[136:139], v[168:171], v[56:59]
	v_mfma_f32_16x16x32_bf16 v[52:55], v[128:131], v[176:179], v[52:55]
	v_mfma_f32_16x16x32_bf16 v[48:51], v[136:139], v[176:179], v[48:51]
	v_mfma_f32_16x16x32_bf16 v[44:47], v[128:131], v[184:187], v[44:47]
	v_mfma_f32_16x16x32_bf16 v[40:43], v[136:139], v[184:187], v[40:43]
	v_mfma_f32_16x16x32_bf16 v[36:39], v[128:131], v[192:195], v[36:39]
	v_mfma_f32_16x16x32_bf16 v[32:35], v[136:139], v[192:195], v[32:35]
	v_mfma_f32_16x16x32_bf16 v[60:63], v[132:135], v[172:175], v[60:63]
	v_mfma_f32_16x16x32_bf16 v[56:59], v[140:143], v[172:175], v[56:59]
	v_mfma_f32_16x16x32_bf16 v[52:55], v[132:135], v[180:183], v[52:55]
	v_mfma_f32_16x16x32_bf16 v[48:51], v[140:143], v[180:183], v[48:51]
	v_mfma_f32_16x16x32_bf16 v[44:47], v[132:135], v[188:191], v[44:47]
	v_mfma_f32_16x16x32_bf16 v[40:43], v[140:143], v[188:191], v[40:43]
	v_mfma_f32_16x16x32_bf16 v[36:39], v[132:135], v[196:199], v[36:39]
	v_mfma_f32_16x16x32_bf16 v[32:35], v[140:143], v[196:199], v[32:35]
	v_mfma_f32_16x16x32_bf16 v[28:31], v[144:147], v[168:171], v[28:31]
	v_mfma_f32_16x16x32_bf16 v[24:27], v[152:155], v[168:171], v[24:27]
	v_mfma_f32_16x16x32_bf16 v[20:23], v[144:147], v[176:179], v[20:23]
	v_mfma_f32_16x16x32_bf16 v[16:19], v[152:155], v[176:179], v[16:19]
	v_mfma_f32_16x16x32_bf16 v[12:15], v[144:147], v[184:187], v[12:15]
	v_mfma_f32_16x16x32_bf16 v[8:11], v[152:155], v[184:187], v[8:11]
	v_mfma_f32_16x16x32_bf16 v[4:7], v[144:147], v[192:195], v[4:7]
	v_mfma_f32_16x16x32_bf16 v[0:3], v[152:155], v[192:195], v[0:3]
	v_mfma_f32_16x16x32_bf16 v[28:31], v[148:151], v[172:175], v[28:31]
	v_mfma_f32_16x16x32_bf16 v[24:27], v[156:159], v[172:175], v[24:27]
	v_mfma_f32_16x16x32_bf16 v[20:23], v[148:151], v[180:183], v[20:23]
	v_mfma_f32_16x16x32_bf16 v[16:19], v[156:159], v[180:183], v[16:19]
	v_mfma_f32_16x16x32_bf16 v[12:15], v[148:151], v[188:191], v[12:15]
	v_mfma_f32_16x16x32_bf16 v[8:11], v[156:159], v[188:191], v[8:11]
	v_mfma_f32_16x16x32_bf16 v[4:7], v[148:151], v[196:199], v[4:7]
	v_mfma_f32_16x16x32_bf16 v[0:3], v[156:159], v[196:199], v[0:3]
	s_barrier
	s_andn2_b64 vcc, exec, s[8:9]
	s_cbranch_vccnz .LBB0_907
	s_barrier

; #define PG8_STAGE(bufoff, gbase, voff) do { _Pragma("unroll") for (int _i = 0; _i < 2; ++_i) \
;         __builtin_amdgcn_global_load_lds((const unsigned*)((const char*)(gbase) + (voff)[_i]), (PG8_LAS unsigned*)(lds + (bufoff) + ldsw + _i * 8192), 16, 0, 0); } while (0)
; #define PG8_LDA(dst, b, h) do { _Pragma("unroll") for (int m = 0; m < 4; ++m) _Pragma("unroll") for (int k = 0; k < 2; ++k) dst[m][k] = *(const PG8_LAS bf16x8*)(lds + PG8_SA(b, h) + aoff + m * 2048 + k * 1024); } while (0)
; #define PG8_LDB(dst, b, h) do { _Pragma("unroll") for (int n = 0; n < 2; ++n) _Pragma("unroll") for (int k = 0; k < 2; ++k) dst[n][k] = *(const PG8_LAS bf16x8*)(lds + PG8_SB(b, h) + boff + n * 2048 + k * 1024); } while (0)
; template <class Epi, class Sched, bool ALIGN_EPI = false, bool SP2 = false>
; __device__ __forceinline__ void gemm_phase(PG8_LAS unsigned char* lds, const Gemm g, const Sched& S, const Epi& E) {
;     ...
;         for (int t = 0; t < nt; t += 2) {
;             const bool last = (t == nt - 2);
;             const char* a1 = cA + (size_t)(t + 1) * kstep;
;             const char* a2 = last ? nA : cA + (size_t)(t + 2) * kstep; const char* b2 = last ? nB : cB + (size_t)(t + 2) * kstep;
;             const char* a3 = a2 + kstep; const char* b3 = b2 + kstep;
;             if (last && has_next) S.a_ready(nxt);
;             if constexpr (SP2) {
;             PG8_LDB(B0, 0, 0); PG8_LDB(B1, 0, 1); PG8_SCHED; PG8_LDA(At, 0, 0); PG8_STAGE(PG8_SA(1, 1), a1 + hstep, voffA);
;             PG8_WAIT_V(8); PG8_WAIT_L(0); PG8_BAR; PG8_MMA(0, 0, At, B0); PG8_MMA(0, 1, At, B1); PG8_BAR; PG8_SCHED;
;             PG8_LDA(At, 0, 1); PG8_STAGE(PG8_SB(0, 0), b2, voffB); PG8_STAGE(PG8_SB(0, 1), b2 + hstep, voffB); PG8_STAGE(PG8_SA(0, 0), a2, voffA);
;             PG8_WAIT_V(8); PG8_WAIT_L(0); PG8_BAR; PG8_MMA(1, 0, At, B0); PG8_MMA(1, 1, At, B1); PG8_BAR; PG8_SCHED;
;             PG8_LDB(B0, 1, 0); PG8_LDB(B1, 1, 1); PG8_SCHED; PG8_LDA(At, 1, 0); PG8_STAGE(PG8_SA(0, 1), a2 + hstep, voffA);
;             PG8_WAIT_V(8); PG8_WAIT_L(0); PG8_BAR; PG8_MMA(0, 0, At, B0); PG8_MMA(0, 1, At, B1); PG8_BAR; PG8_SCHED;
;             PG8_LDA(At, 1, 1); PG8_STAGE(PG8_SB(1, 0), b3, voffB); PG8_STAGE(PG8_SB(1, 1), b3 + hstep, voffB); PG8_STAGE(PG8_SA(1, 0), a3, voffA);
;             PG8_WAIT_V(8); PG8_WAIT_L(0); PG8_BAR; PG8_MMA(1, 0, At, B0); PG8_MMA(1, 1, At, B1); PG8_BAR; PG8_SCHED;
.LBB0_1130:
	s_add_u32 s10, s6, 0x4000
	s_addc_u32 s11, s7, 0
	s_cmp_eq_u32 s40, 12
	s_cselect_b32 s86, s9, s10
	s_cselect_b32 s87, s5, s11
	s_cselect_b32 s84, s23, s30
	s_cselect_b32 s85, s22, s37
	s_add_u32 s10, s86, 0x8000
	s_addc_u32 s11, s87, 0
	s_add_i32 s77, 0, 0x10000
	s_add_i32 s79, 0, 0x14000
	v_add_u32_e32 v32, s77, v192
	v_add_u32_e32 v60, s79, v192
	ds_read_b128 v[16:19], v32
	ds_read_b128 v[20:23], v32 offset:1024
	ds_read_b128 v[24:27], v32 offset:2048
	ds_read_b128 v[32:35], v32 offset:3072
	ds_read_b128 v[48:51], v60
	ds_read_b128 v[52:55], v60 offset:1024
	ds_read_b128 v[56:59], v60 offset:2048
	ds_read_b128 v[60:63], v60 offset:3072
	s_add_i32 m0, s33, 0xc000
	ds_read_b128 v[160:163], v193
	ds_read_b128 v[164:167], v193 offset:1024
	ds_read_b128 v[180:183], v193 offset:2048
	ds_read_b128 v[184:187], v193 offset:3072
	ds_read_b128 v[188:191], v193 offset:4096
	ds_read_b128 v[194:197], v193 offset:5120
	ds_read_b128 v[198:201], v193 offset:6144
	ds_read_b128 v[202:205], v193 offset:7168
	global_load_lds_dwordx4 v176, s[6:7]
	s_add_i32 m0, s33, 0xe000
	s_nop 0
	global_load_lds_dwordx4 v178, s[6:7]
	s_waitcnt vmcnt(8)
	s_waitcnt lgkmcnt(0)
	s_barrier
	s_waitcnt lgkmcnt(0)
	v_mfma_f32_16x16x32_bf16 v[156:159], v[16:19], v[160:163], v[156:159]
	v_mfma_f32_16x16x32_bf16 v[152:155], v[24:27], v[160:163], v[152:155]
	v_mfma_f32_16x16x32_bf16 v[140:143], v[16:19], v[180:183], v[140:143]
	v_mfma_f32_16x16x32_bf16 v[136:139], v[24:27], v[180:183], v[136:139]
	v_mfma_f32_16x16x32_bf16 v[124:127], v[16:19], v[188:191], v[124:127]
	v_mfma_f32_16x16x32_bf16 v[120:123], v[24:27], v[188:191], v[120:123]
	v_mfma_f32_16x16x32_bf16 v[108:111], v[16:19], v[198:201], v[108:111]
	v_mfma_f32_16x16x32_bf16 v[104:107], v[24:27], v[198:201], v[104:107]
	v_mfma_f32_16x16x32_bf16 v[156:159], v[20:23], v[164:167], v[156:159]
	v_mfma_f32_16x16x32_bf16 v[152:155], v[32:35], v[164:167], v[152:155]
	v_mfma_f32_16x16x32_bf16 v[140:143], v[20:23], v[184:187], v[140:143]
	v_mfma_f32_16x16x32_bf16 v[136:139], v[32:35], v[184:187], v[136:139]
	v_mfma_f32_16x16x32_bf16 v[124:127], v[20:23], v[194:197], v[124:127]
	v_mfma_f32_16x16x32_bf16 v[120:123], v[32:35], v[194:197], v[120:123]
	v_mfma_f32_16x16x32_bf16 v[108:111], v[20:23], v[202:205], v[108:111]
	v_mfma_f32_16x16x32_bf16 v[104:107], v[32:35], v[202:205], v[104:107]
	v_mfma_f32_16x16x32_bf16 v[148:151], v[48:51], v[160:163], v[148:151]
	v_mfma_f32_16x16x32_bf16 v[144:147], v[56:59], v[160:163], v[144:147]
	v_mfma_f32_16x16x32_bf16 v[132:135], v[48:51], v[180:183], v[132:135]
	v_mfma_f32_16x16x32_bf16 v[128:131], v[56:59], v[180:183], v[128:131]
	v_mfma_f32_16x16x32_bf16 v[116:119], v[48:51], v[188:191], v[116:119]
	v_mfma_f32_16x16x32_bf16 v[112:115], v[56:59], v[188:191], v[112:115]
	v_mfma_f32_16x16x32_bf16 v[100:103], v[48:51], v[198:201], v[100:103]
	v_mfma_f32_16x16x32_bf16 v[96:99], v[56:59], v[198:201], v[96:99]
	v_mfma_f32_16x16x32_bf16 v[148:151], v[52:55], v[164:167], v[148:151]
	v_mfma_f32_16x16x32_bf16 v[144:147], v[60:63], v[164:167], v[144:147]
	v_mfma_f32_16x16x32_bf16 v[132:135], v[52:55], v[184:187], v[132:135]
	v_mfma_f32_16x16x32_bf16 v[128:131], v[60:63], v[184:187], v[128:131]
	v_mfma_f32_16x16x32_bf16 v[116:119], v[52:55], v[194:197], v[116:119]
	v_mfma_f32_16x16x32_bf16 v[112:115], v[60:63], v[194:197], v[112:115]
	v_mfma_f32_16x16x32_bf16 v[100:103], v[52:55], v[202:205], v[100:103]
	v_mfma_f32_16x16x32_bf16 v[96:99], v[60:63], v[202:205], v[96:99]
	s_barrier
	s_add_i32 s77, s77, s57
	s_mov_b32 m0, s77
	ds_read_b128 v[160:163], v193 offset:16384
	ds_read_b128 v[164:167], v193 offset:17408
	ds_read_b128 v[180:183], v193 offset:18432
	ds_read_b128 v[184:187], v193 offset:19456
	ds_read_b128 v[188:191], v193 offset:20480
	ds_read_b128 v[194:197], v193 offset:21504
	ds_read_b128 v[198:201], v193 offset:22528
	ds_read_b128 v[202:205], v193 offset:23552
	global_load_lds_dwordx4 v170, s[84:85]
	s_add_i32 m0, s77, 0x2000
	s_add_u32 s88, s84, 0x4000
	s_addc_u32 s89, s85, 0
	s_add_i32 s77, s79, s57
	global_load_lds_dwordx4 v174, s[84:85]
	s_mov_b32 m0, s77
	s_nop 0
	global_load_lds_dwordx4 v170, s[88:89]
	s_add_i32 m0, s77, 0x2000
	s_nop 0
	global_load_lds_dwordx4 v174, s[88:89]
	s_mov_b32 m0, s33
	s_nop 0
	global_load_lds_dwordx4 v168, s[86:87]
	s_mov_b32 m0, s42
	s_nop 0
	global_load_lds_dwordx4 v172, s[86:87]
	s_waitcnt vmcnt(8)
	s_waitcnt lgkmcnt(0)
	s_barrier
	s_waitcnt lgkmcnt(0)
	v_mfma_f32_16x16x32_bf16 v[92:95], v[16:19], v[160:163], v[92:95]
	v_mfma_f32_16x16x32_bf16 v[88:91], v[24:27], v[160:163], v[88:91]
	v_mfma_f32_16x16x32_bf16 v[76:79], v[16:19], v[180:183], v[76:79]
	v_mfma_f32_16x16x32_bf16 v[72:75], v[24:27], v[180:183], v[72:75]
	v_mfma_f32_16x16x32_bf16 v[44:47], v[16:19], v[188:191], v[44:47]
	v_mfma_f32_16x16x32_bf16 v[40:43], v[24:27], v[188:191], v[40:43]
	v_mfma_f32_16x16x32_bf16 v[12:15], v[16:19], v[198:201], v[12:15]
	v_mfma_f32_16x16x32_bf16 v[8:11], v[24:27], v[198:201], v[8:11]
	v_mfma_f32_16x16x32_bf16 v[92:95], v[20:23], v[164:167], v[92:95]
	v_mfma_f32_16x16x32_bf16 v[88:91], v[32:35], v[164:167], v[88:91]
	v_mfma_f32_16x16x32_bf16 v[76:79], v[20:23], v[184:187], v[76:79]
	v_mfma_f32_16x16x32_bf16 v[72:75], v[32:35], v[184:187], v[72:75]
	v_mfma_f32_16x16x32_bf16 v[44:47], v[20:23], v[194:197], v[44:47]
	v_mfma_f32_16x16x32_bf16 v[40:43], v[32:35], v[194:197], v[40:43]
	v_mfma_f32_16x16x32_bf16 v[12:15], v[20:23], v[202:205], v[12:15]
	v_mfma_f32_16x16x32_bf16 v[8:11], v[32:35], v[202:205], v[8:11]
	v_mfma_f32_16x16x32_bf16 v[36:39], v[48:51], v[188:191], v[36:39]
	v_mfma_f32_16x16x32_bf16 v[28:31], v[56:59], v[188:191], v[28:31]
	v_mfma_f32_16x16x32_bf16 v[4:7], v[48:51], v[198:201], v[4:7]
	v_mfma_f32_16x16x32_bf16 v[0:3], v[56:59], v[198:201], v[0:3]
	v_mfma_f32_16x16x32_bf16 v[16:19], v[48:51], v[160:163], v[84:87]
	v_mfma_f32_16x16x32_bf16 v[20:23], v[56:59], v[160:163], v[80:83]
	v_mfma_f32_16x16x32_bf16 v[24:27], v[48:51], v[180:183], v[68:71]
	v_mfma_f32_16x16x32_bf16 v[32:35], v[56:59], v[180:183], v[64:67]
	v_mfma_f32_16x16x32_bf16 v[36:39], v[52:55], v[194:197], v[36:39]
	v_mfma_f32_16x16x32_bf16 v[28:31], v[60:63], v[194:197], v[28:31]
	v_mfma_f32_16x16x32_bf16 v[4:7], v[52:55], v[202:205], v[4:7]
	v_mfma_f32_16x16x32_bf16 v[0:3], v[60:63], v[202:205], v[0:3]
	v_mfma_f32_16x16x32_bf16 v[16:19], v[52:55], v[164:167], v[16:19]
	v_mfma_f32_16x16x32_bf16 v[20:23], v[60:63], v[164:167], v[20:23]
	v_mfma_f32_16x16x32_bf16 v[24:27], v[52:55], v[184:187], v[24:27]
	v_mfma_f32_16x16x32_bf16 v[32:35], v[60:63], v[184:187], v[32:35]
	s_barrier
; #define PG8_STAGE(bufoff, gbase, voff) do { _Pragma("unroll") for (int _i = 0; _i < 2; ++_i) \
;         __builtin_amdgcn_global_load_lds((const unsigned*)((const char*)(gbase) + (voff)[_i]), (PG8_LAS unsigned*)(lds + (bufoff) + ldsw + _i * 8192), 16, 0, 0); } while (0)
; #define PG8_LDA(dst, b, h) do { _Pragma("unroll") for (int m = 0; m < 4; ++m) _Pragma("unroll") for (int k = 0; k < 2; ++k) dst[m][k] = *(const PG8_LAS bf16x8*)(lds + PG8_SA(b, h) + aoff + m * 2048 + k * 1024); } while (0)
; #define PG8_LDB(dst, b, h) do { _Pragma("unroll") for (int n = 0; n < 2; ++n) _Pragma("unroll") for (int k = 0; k < 2; ++k) dst[n][k] = *(const PG8_LAS bf16x8*)(lds + PG8_SB(b, h) + boff + n * 2048 + k * 1024); } while (0)
; #define PG8_MMA(ai, bj, At, Bt) do { __builtin_amdgcn_s_setprio(1); _Pragma("unroll") for (int m = 0; m < 4; ++m) _Pragma("unroll") for (int n = 0; n < 2; ++n) _Pragma("unroll") for (int k = 0; k < 2; ++k) \
;         acc[ai][bj][m][n] = __builtin_amdgcn_mfma_f32_16x16x32_bf16(Bt[n][k], At[m][k], acc[ai][bj][m][n], 0, 0, 0); __builtin_amdgcn_s_setprio(0); } while (0)
; template <class Epi, class Sched, bool ALIGN_EPI = false, bool SP2 = false>
; __device__ __forceinline__ void gemm_phase(PG8_LAS unsigned char* lds, const Gemm g, const Sched& S, const Epi& E) {
;     ...
;             PG8_LDB(B0, 0, 0); PG8_LDB(B1, 0, 1); PG8_SCHED; PG8_LDA(At, 0, 0); PG8_STAGE(PG8_SA(1, 1), a1 + hstep, voffA);
;             PG8_WAIT_V(8); PG8_WAIT_L(0); PG8_BAR; PG8_MMA(0, 0, At, B0); PG8_MMA(0, 1, At, B1); PG8_BAR; PG8_SCHED;
;             PG8_LDA(At, 0, 1); PG8_STAGE(PG8_SB(0, 0), b2, voffB); PG8_STAGE(PG8_SB(0, 1), b2 + hstep, voffB); PG8_STAGE(PG8_SA(0, 0), a2, voffA);
;             PG8_WAIT_V(8); PG8_WAIT_L(0); PG8_BAR; PG8_MMA(1, 0, At, B0); PG8_MMA(1, 1, At, B1); PG8_BAR; PG8_SCHED;
;             PG8_LDB(B0, 1, 0); PG8_LDB(B1, 1, 1); PG8_SCHED; PG8_LDA(At, 1, 0); PG8_STAGE(PG8_SA(0, 1), a2 + hstep, voffA);
;             PG8_WAIT_V(8); PG8_WAIT_L(0); PG8_BAR; PG8_MMA(0, 0, At, B0); PG8_MMA(0, 1, At, B1); PG8_BAR; PG8_SCHED;
;             PG8_LDA(At, 1, 1); PG8_STAGE(PG8_SB(1, 0), b3, voffB); PG8_STAGE(PG8_SB(1, 1), b3 + hstep, voffB); PG8_STAGE(PG8_SA(1, 0), a3, voffA);
;             PG8_WAIT_V(8); PG8_WAIT_L(0); PG8_BAR; PG8_MMA(1, 0, At, B0); PG8_MMA(1, 1, At, B1); PG8_BAR; PG8_SCHED;
;     ...
;         if constexpr (ALIGN_EPI) { if (wr == 0) PG8_BAR; }
	s_add_i32 s77, 0, 0x18000
	s_add_i32 s79, 0, 0x1c000
	v_add_u32_e32 v60, s77, v192
	v_add_u32_e32 v64, s79, v192
	ds_read_b128 v[48:51], v60
	ds_read_b128 v[52:55], v60 offset:1024
	ds_read_b128 v[56:59], v60 offset:2048
	ds_read_b128 v[60:63], v60 offset:3072
	ds_read_b128 v[160:163], v64
	ds_read_b128 v[164:167], v64 offset:1024
	ds_read_b128 v[180:183], v64 offset:2048
	ds_read_b128 v[184:187], v64 offset:3072
	s_add_u32 s86, s86, 0x4000
	s_addc_u32 s87, s87, 0
	s_mov_b32 m0, s64
	ds_read_b128 v[64:67], v193 offset:32768
	ds_read_b128 v[68:71], v193 offset:33792
	ds_read_b128 v[80:83], v193 offset:34816
	ds_read_b128 v[84:87], v193 offset:35840
	ds_read_b128 v[188:191], v193 offset:36864
	ds_read_b128 v[194:197], v193 offset:37888
	ds_read_b128 v[198:201], v193 offset:38912
	ds_read_b128 v[202:205], v193 offset:39936
	global_load_lds_dwordx4 v168, s[86:87]
	s_mov_b32 m0, s65
	s_nop 0
	global_load_lds_dwordx4 v172, s[86:87]
	s_waitcnt vmcnt(8)
	s_waitcnt lgkmcnt(0)
	s_barrier
	s_waitcnt lgkmcnt(0)
	v_mfma_f32_16x16x32_bf16 v[156:159], v[48:51], v[64:67], v[156:159]
	v_mfma_f32_16x16x32_bf16 v[152:155], v[56:59], v[64:67], v[152:155]
	v_mfma_f32_16x16x32_bf16 v[140:143], v[48:51], v[80:83], v[140:143]
	v_mfma_f32_16x16x32_bf16 v[136:139], v[56:59], v[80:83], v[136:139]
	v_mfma_f32_16x16x32_bf16 v[124:127], v[48:51], v[188:191], v[124:127]
	v_mfma_f32_16x16x32_bf16 v[120:123], v[56:59], v[188:191], v[120:123]
	v_mfma_f32_16x16x32_bf16 v[108:111], v[48:51], v[198:201], v[108:111]
	v_mfma_f32_16x16x32_bf16 v[104:107], v[56:59], v[198:201], v[104:107]
	v_mfma_f32_16x16x32_bf16 v[156:159], v[52:55], v[68:71], v[156:159]
	v_mfma_f32_16x16x32_bf16 v[152:155], v[60:63], v[68:71], v[152:155]
	v_mfma_f32_16x16x32_bf16 v[140:143], v[52:55], v[84:87], v[140:143]
	v_mfma_f32_16x16x32_bf16 v[136:139], v[60:63], v[84:87], v[136:139]
	v_mfma_f32_16x16x32_bf16 v[124:127], v[52:55], v[194:197], v[124:127]
	v_mfma_f32_16x16x32_bf16 v[120:123], v[60:63], v[194:197], v[120:123]
	v_mfma_f32_16x16x32_bf16 v[108:111], v[52:55], v[202:205], v[108:111]
	v_mfma_f32_16x16x32_bf16 v[104:107], v[60:63], v[202:205], v[104:107]
	v_mfma_f32_16x16x32_bf16 v[148:151], v[160:163], v[64:67], v[148:151]
	v_mfma_f32_16x16x32_bf16 v[64:67], v[180:183], v[64:67], v[144:147]
	v_mfma_f32_16x16x32_bf16 v[144:147], v[184:187], v[68:71], v[64:67]
	v_mfma_f32_16x16x32_bf16 v[64:67], v[160:163], v[80:83], v[132:135]
	v_mfma_f32_16x16x32_bf16 v[132:135], v[164:167], v[84:87], v[64:67]
	v_mfma_f32_16x16x32_bf16 v[64:67], v[180:183], v[80:83], v[128:131]
	v_mfma_f32_16x16x32_bf16 v[128:131], v[184:187], v[84:87], v[64:67]
	v_mfma_f32_16x16x32_bf16 v[64:67], v[160:163], v[188:191], v[116:119]
	v_mfma_f32_16x16x32_bf16 v[116:119], v[164:167], v[194:197], v[64:67]
	v_mfma_f32_16x16x32_bf16 v[64:67], v[180:183], v[188:191], v[112:115]
	v_mfma_f32_16x16x32_bf16 v[112:115], v[184:187], v[194:197], v[64:67]
	v_mfma_f32_16x16x32_bf16 v[64:67], v[160:163], v[198:201], v[100:103]
	v_mfma_f32_16x16x32_bf16 v[100:103], v[164:167], v[202:205], v[64:67]
	v_mfma_f32_16x16x32_bf16 v[64:67], v[180:183], v[198:201], v[96:99]
	v_mfma_f32_16x16x32_bf16 v[148:151], v[164:167], v[68:71], v[148:151]
	v_mfma_f32_16x16x32_bf16 v[96:99], v[184:187], v[202:205], v[64:67]
	s_barrier
	s_add_u32 s86, s84, 0x8000
	s_addc_u32 s87, s85, 0
	s_add_i32 s77, s77, s57
	s_mov_b32 m0, s77
	ds_read_b128 v[64:67], v193 offset:49152
	ds_read_b128 v[68:71], v193 offset:50176
	ds_read_b128 v[188:191], v193 offset:51200
	ds_read_b128 v[194:197], v193 offset:52224
	ds_read_b128 v[198:201], v193 offset:53248
	ds_read_b128 v[202:205], v193 offset:54272
	ds_read_b128 v[206:209], v193 offset:55296
	ds_read_b128 v[210:213], v193 offset:56320
	global_load_lds_dwordx4 v170, s[86:87]
	s_add_i32 m0, s77, 0x2000
	s_add_u32 s84, s84, 0xc000
	s_addc_u32 s85, s85, 0
	s_add_i32 s77, s79, s57
	global_load_lds_dwordx4 v174, s[86:87]
	s_mov_b32 m0, s77
	s_nop 0
	global_load_lds_dwordx4 v170, s[84:85]
	s_add_i32 m0, s77, 0x2000
	s_nop 0
	global_load_lds_dwordx4 v174, s[84:85]
	s_mov_b32 m0, s53
	s_nop 0
	global_load_lds_dwordx4 v168, s[10:11]
	s_mov_b32 m0, s27
	s_nop 0
	global_load_lds_dwordx4 v172, s[10:11]
	s_waitcnt vmcnt(8)
	s_waitcnt lgkmcnt(0)
	s_barrier
	s_waitcnt lgkmcnt(0)
	v_mfma_f32_16x16x32_bf16 v[80:83], v[48:51], v[64:67], v[92:95]
	v_mfma_f32_16x16x32_bf16 v[92:95], v[52:55], v[68:71], v[80:83]
	v_mfma_f32_16x16x32_bf16 v[80:83], v[56:59], v[64:67], v[88:91]
	v_mfma_f32_16x16x32_bf16 v[76:79], v[48:51], v[188:191], v[76:79]
	v_mfma_f32_16x16x32_bf16 v[72:75], v[56:59], v[188:191], v[72:75]
	v_mfma_f32_16x16x32_bf16 v[44:47], v[48:51], v[198:201], v[44:47]
	v_mfma_f32_16x16x32_bf16 v[40:43], v[56:59], v[198:201], v[40:43]
	v_mfma_f32_16x16x32_bf16 v[12:15], v[48:51], v[206:209], v[12:15]
	v_mfma_f32_16x16x32_bf16 v[8:11], v[56:59], v[206:209], v[8:11]
	v_mfma_f32_16x16x32_bf16 v[88:91], v[60:63], v[68:71], v[80:83]
	v_mfma_f32_16x16x32_bf16 v[76:79], v[52:55], v[194:197], v[76:79]
	v_mfma_f32_16x16x32_bf16 v[72:75], v[60:63], v[194:197], v[72:75]
	v_mfma_f32_16x16x32_bf16 v[44:47], v[52:55], v[202:205], v[44:47]
	v_mfma_f32_16x16x32_bf16 v[40:43], v[60:63], v[202:205], v[40:43]
	v_mfma_f32_16x16x32_bf16 v[12:15], v[52:55], v[210:213], v[12:15]
	v_mfma_f32_16x16x32_bf16 v[8:11], v[60:63], v[210:213], v[8:11]
	v_mfma_f32_16x16x32_bf16 v[16:19], v[160:163], v[64:67], v[16:19]
	v_mfma_f32_16x16x32_bf16 v[84:87], v[164:167], v[68:71], v[16:19]
	v_mfma_f32_16x16x32_bf16 v[16:19], v[180:183], v[64:67], v[20:23]
	v_mfma_f32_16x16x32_bf16 v[80:83], v[184:187], v[68:71], v[16:19]
	v_mfma_f32_16x16x32_bf16 v[16:19], v[160:163], v[188:191], v[24:27]
	v_mfma_f32_16x16x32_bf16 v[68:71], v[164:167], v[194:197], v[16:19]
	v_mfma_f32_16x16x32_bf16 v[16:19], v[180:183], v[188:191], v[32:35]
	v_mfma_f32_16x16x32_bf16 v[64:67], v[184:187], v[194:197], v[16:19]
	v_mfma_f32_16x16x32_bf16 v[16:19], v[160:163], v[198:201], v[36:39]
	v_mfma_f32_16x16x32_bf16 v[36:39], v[164:167], v[202:205], v[16:19]
	v_mfma_f32_16x16x32_bf16 v[16:19], v[180:183], v[198:201], v[28:31]
	v_mfma_f32_16x16x32_bf16 v[4:7], v[160:163], v[206:209], v[4:7]
	v_mfma_f32_16x16x32_bf16 v[0:3], v[180:183], v[206:209], v[0:3]
	v_mfma_f32_16x16x32_bf16 v[28:31], v[184:187], v[202:205], v[16:19]
	v_mfma_f32_16x16x32_bf16 v[4:7], v[164:167], v[210:213], v[4:7]
	v_mfma_f32_16x16x32_bf16 v[0:3], v[184:187], v[210:213], v[0:3]
	s_barrier
	s_add_i32 s40, s40, 2
	s_add_u32 s6, s6, 0x10000
	s_addc_u32 s7, s7, 0
	s_add_u32 s30, s30, 0x10000
	s_addc_u32 s37, s37, 0
	s_cmp_gt_u32 s40, 13
	s_cbranch_scc0 .LBB0_1130
	s_and_b64 vcc, exec, s[70:71]
	s_cbranch_vccz .LBB0_1133
	s_barrier

; #define PG8_STAGE(bufoff, gbase, voff) do { _Pragma("unroll") for (int _i = 0; _i < 2; ++_i) \
;         __builtin_amdgcn_global_load_lds((const unsigned*)((const char*)(gbase) + (voff)[_i]), (PG8_LAS unsigned*)(lds + (bufoff) + ldsw + _i * 8192), 16, 0, 0); } while (0)
; #define PG8_LDA(dst, b, h) do { _Pragma("unroll") for (int m = 0; m < 4; ++m) _Pragma("unroll") for (int k = 0; k < 2; ++k) dst[m][k] = *(const PG8_LAS bf16x8*)(lds + PG8_SA(b, h) + aoff + m * 2048 + k * 1024); } while (0)
; #define PG8_LDB(dst, b, h) do { _Pragma("unroll") for (int n = 0; n < 2; ++n) _Pragma("unroll") for (int k = 0; k < 2; ++k) dst[n][k] = *(const PG8_LAS bf16x8*)(lds + PG8_SB(b, h) + boff + n * 2048 + k * 1024); } while (0)
; template <class Epi, class Sched, bool ALIGN_EPI = false, bool SP2 = false>
; __device__ __forceinline__ void gemm_phase(PG8_LAS unsigned char* lds, const Gemm g, const Sched& S, const Epi& E) {
;     ...
;         for (int t = 0; t < nt; t += 2) {
;             const bool last = (t == nt - 2);
;             const char* a1 = cA + (size_t)(t + 1) * kstep;
;             const char* a2 = last ? nA : cA + (size_t)(t + 2) * kstep; const char* b2 = last ? nB : cB + (size_t)(t + 2) * kstep;
;             const char* a3 = a2 + kstep; const char* b3 = b2 + kstep;
;             if (last && has_next) S.a_ready(nxt);
;             if constexpr (SP2) {
;             PG8_LDB(B0, 0, 0); PG8_LDB(B1, 0, 1); PG8_SCHED; PG8_LDA(At, 0, 0); PG8_STAGE(PG8_SA(1, 1), a1 + hstep, voffA);
;             PG8_WAIT_V(8); PG8_WAIT_L(0); PG8_BAR; PG8_MMA(0, 0, At, B0); PG8_MMA(0, 1, At, B1); PG8_BAR; PG8_SCHED;
;             PG8_LDA(At, 0, 1); PG8_STAGE(PG8_SB(0, 0), b2, voffB); PG8_STAGE(PG8_SB(0, 1), b2 + hstep, voffB); PG8_STAGE(PG8_SA(0, 0), a2, voffA);
;             PG8_WAIT_V(8); PG8_WAIT_L(0); PG8_BAR; PG8_MMA(1, 0, At, B0); PG8_MMA(1, 1, At, B1); PG8_BAR; PG8_SCHED;
;             PG8_LDB(B0, 1, 0); PG8_LDB(B1, 1, 1); PG8_SCHED; PG8_LDA(At, 1, 0); PG8_STAGE(PG8_SA(0, 1), a2 + hstep, voffA);
;             PG8_WAIT_V(8); PG8_WAIT_L(0); PG8_BAR; PG8_MMA(0, 0, At, B0); PG8_MMA(0, 1, At, B1); PG8_BAR; PG8_SCHED;
;             PG8_LDA(At, 1, 1); PG8_STAGE(PG8_SB(1, 0), b3, voffB); PG8_STAGE(PG8_SB(1, 1), b3 + hstep, voffB); PG8_STAGE(PG8_SA(1, 0), a3, voffA);
;             PG8_WAIT_V(8); PG8_WAIT_L(0); PG8_BAR; PG8_MMA(1, 0, At, B0); PG8_MMA(1, 1, At, B1); PG8_BAR; PG8_SCHED;
.LBB0_1322:
	s_add_i32 s75, s18, 2
	s_add_u32 s19, s16, 0x4000
	s_addc_u32 s20, s17, 0
	s_cmp_eq_u32 s59, s18
	s_cselect_b32 s64, s0, s19
	s_cselect_b32 s65, s1, s20
	s_cselect_b32 s20, s14, s66
	s_cselect_b32 s21, s15, s67
	s_add_u32 s18, s64, 0x8000
	s_addc_u32 s19, s65, 0
	s_add_i32 s76, 0, 0x10000
	s_add_i32 s78, 0, 0x14000
	v_add_u32_e32 v108, s76, v206
	v_add_u32_e32 v156, s78, v206
	ds_read_b128 v[80:83], v108
	ds_read_b128 v[84:87], v108 offset:1024
	ds_read_b128 v[104:107], v108 offset:2048
	ds_read_b128 v[108:111], v108 offset:3072
	ds_read_b128 v[128:131], v156
	ds_read_b128 v[136:139], v156 offset:1024
	ds_read_b128 v[152:155], v156 offset:2048
	ds_read_b128 v[156:159], v156 offset:3072
	s_add_i32 m0, s41, 0xc000
	ds_read_b128 v[160:163], v207
	ds_read_b128 v[164:167], v207 offset:1024
	ds_read_b128 v[168:171], v207 offset:2048
	ds_read_b128 v[172:175], v207 offset:3072
	ds_read_b128 v[176:179], v207 offset:4096
	ds_read_b128 v[180:183], v207 offset:5120
	ds_read_b128 v[198:201], v207 offset:6144
	ds_read_b128 v[202:205], v207 offset:7168
	global_load_lds_dwordx4 v194, s[16:17]
	s_add_i32 m0, s41, 0xe000
	s_nop 0
	global_load_lds_dwordx4 v196, s[16:17]
	s_waitcnt vmcnt(8)
	s_waitcnt lgkmcnt(0)
	s_barrier
	s_waitcnt lgkmcnt(0)
	v_mfma_f32_16x16x32_bf16 v[148:151], v[80:83], v[160:163], v[148:151]
	v_mfma_f32_16x16x32_bf16 v[144:147], v[104:107], v[160:163], v[144:147]
	v_mfma_f32_16x16x32_bf16 v[124:127], v[80:83], v[168:171], v[124:127]
	v_mfma_f32_16x16x32_bf16 v[120:123], v[104:107], v[168:171], v[120:123]
	v_mfma_f32_16x16x32_bf16 v[100:103], v[80:83], v[176:179], v[100:103]
	v_mfma_f32_16x16x32_bf16 v[96:99], v[104:107], v[176:179], v[96:99]
	v_mfma_f32_16x16x32_bf16 v[76:79], v[80:83], v[198:201], v[76:79]
	v_mfma_f32_16x16x32_bf16 v[72:75], v[104:107], v[198:201], v[72:75]
	v_mfma_f32_16x16x32_bf16 v[148:151], v[84:87], v[164:167], v[148:151]
	v_mfma_f32_16x16x32_bf16 v[144:147], v[108:111], v[164:167], v[144:147]
	v_mfma_f32_16x16x32_bf16 v[124:127], v[84:87], v[172:175], v[124:127]
	v_mfma_f32_16x16x32_bf16 v[120:123], v[108:111], v[172:175], v[120:123]
	v_mfma_f32_16x16x32_bf16 v[100:103], v[84:87], v[180:183], v[100:103]
	v_mfma_f32_16x16x32_bf16 v[96:99], v[108:111], v[180:183], v[96:99]
	v_mfma_f32_16x16x32_bf16 v[76:79], v[84:87], v[202:205], v[76:79]
	v_mfma_f32_16x16x32_bf16 v[72:75], v[108:111], v[202:205], v[72:75]
	v_mfma_f32_16x16x32_bf16 v[140:143], v[128:131], v[160:163], v[140:143]
	v_mfma_f32_16x16x32_bf16 v[132:135], v[152:155], v[160:163], v[132:135]
	v_mfma_f32_16x16x32_bf16 v[116:119], v[128:131], v[168:171], v[116:119]
	v_mfma_f32_16x16x32_bf16 v[112:115], v[152:155], v[168:171], v[112:115]
	v_mfma_f32_16x16x32_bf16 v[92:95], v[128:131], v[176:179], v[92:95]
	v_mfma_f32_16x16x32_bf16 v[88:91], v[152:155], v[176:179], v[88:91]
	v_mfma_f32_16x16x32_bf16 v[68:71], v[128:131], v[198:201], v[68:71]
	v_mfma_f32_16x16x32_bf16 v[64:67], v[152:155], v[198:201], v[64:67]
	v_mfma_f32_16x16x32_bf16 v[140:143], v[136:139], v[164:167], v[140:143]
	v_mfma_f32_16x16x32_bf16 v[132:135], v[156:159], v[164:167], v[132:135]
	v_mfma_f32_16x16x32_bf16 v[116:119], v[136:139], v[172:175], v[116:119]
	v_mfma_f32_16x16x32_bf16 v[112:115], v[156:159], v[172:175], v[112:115]
	v_mfma_f32_16x16x32_bf16 v[92:95], v[136:139], v[180:183], v[92:95]
	v_mfma_f32_16x16x32_bf16 v[88:91], v[156:159], v[180:183], v[88:91]
	v_mfma_f32_16x16x32_bf16 v[68:71], v[136:139], v[202:205], v[68:71]
	v_mfma_f32_16x16x32_bf16 v[64:67], v[156:159], v[202:205], v[64:67]
	s_barrier
	s_add_i32 s76, s76, s39
	s_mov_b32 m0, s76
	ds_read_b128 v[160:163], v207 offset:16384
	ds_read_b128 v[164:167], v207 offset:17408
	ds_read_b128 v[168:171], v207 offset:18432
	ds_read_b128 v[172:175], v207 offset:19456
	ds_read_b128 v[176:179], v207 offset:20480
	ds_read_b128 v[180:183], v207 offset:21504
	ds_read_b128 v[198:201], v207 offset:22528
	ds_read_b128 v[202:205], v207 offset:23552
	global_load_lds_dwordx4 v186, s[20:21]
	s_add_i32 m0, s76, 0x2000
	s_add_u32 s76, s20, 0x4000
	s_addc_u32 s77, s21, 0
	s_add_i32 s78, s78, s39
	global_load_lds_dwordx4 v190, s[20:21]
	s_mov_b32 m0, s78
	s_nop 0
	global_load_lds_dwordx4 v186, s[76:77]
	s_add_i32 m0, s78, 0x2000
	s_nop 0
	global_load_lds_dwordx4 v190, s[76:77]
	s_mov_b32 m0, s41
	s_nop 0
	global_load_lds_dwordx4 v184, s[64:65]
	s_mov_b32 m0, s42
	s_nop 0
	global_load_lds_dwordx4 v188, s[64:65]
	s_waitcnt vmcnt(8)
	s_waitcnt lgkmcnt(0)
	s_barrier
	s_waitcnt lgkmcnt(0)
	v_mfma_f32_16x16x32_bf16 v[60:63], v[80:83], v[160:163], v[60:63]
	v_mfma_f32_16x16x32_bf16 v[56:59], v[104:107], v[160:163], v[56:59]
	v_mfma_f32_16x16x32_bf16 v[44:47], v[80:83], v[168:171], v[44:47]
	v_mfma_f32_16x16x32_bf16 v[40:43], v[104:107], v[168:171], v[40:43]
	v_mfma_f32_16x16x32_bf16 v[28:31], v[80:83], v[176:179], v[28:31]
	v_mfma_f32_16x16x32_bf16 v[24:27], v[104:107], v[176:179], v[24:27]
	v_mfma_f32_16x16x32_bf16 v[12:15], v[80:83], v[198:201], v[12:15]
	v_mfma_f32_16x16x32_bf16 v[8:11], v[104:107], v[198:201], v[8:11]
	v_mfma_f32_16x16x32_bf16 v[60:63], v[84:87], v[164:167], v[60:63]
	v_mfma_f32_16x16x32_bf16 v[56:59], v[108:111], v[164:167], v[56:59]
	v_mfma_f32_16x16x32_bf16 v[44:47], v[84:87], v[172:175], v[44:47]
	v_mfma_f32_16x16x32_bf16 v[40:43], v[108:111], v[172:175], v[40:43]
	v_mfma_f32_16x16x32_bf16 v[28:31], v[84:87], v[180:183], v[28:31]
	v_mfma_f32_16x16x32_bf16 v[24:27], v[108:111], v[180:183], v[24:27]
	v_mfma_f32_16x16x32_bf16 v[12:15], v[84:87], v[202:205], v[12:15]
	v_mfma_f32_16x16x32_bf16 v[8:11], v[108:111], v[202:205], v[8:11]
	v_mfma_f32_16x16x32_bf16 v[52:55], v[128:131], v[160:163], v[52:55]
	v_mfma_f32_16x16x32_bf16 v[48:51], v[152:155], v[160:163], v[48:51]
	v_mfma_f32_16x16x32_bf16 v[36:39], v[128:131], v[168:171], v[36:39]
	v_mfma_f32_16x16x32_bf16 v[32:35], v[152:155], v[168:171], v[32:35]
	v_mfma_f32_16x16x32_bf16 v[20:23], v[128:131], v[176:179], v[20:23]
	v_mfma_f32_16x16x32_bf16 v[16:19], v[152:155], v[176:179], v[16:19]
	v_mfma_f32_16x16x32_bf16 v[4:7], v[128:131], v[198:201], v[4:7]
	v_mfma_f32_16x16x32_bf16 v[0:3], v[152:155], v[198:201], v[0:3]
	v_mfma_f32_16x16x32_bf16 v[52:55], v[136:139], v[164:167], v[52:55]
	v_mfma_f32_16x16x32_bf16 v[48:51], v[156:159], v[164:167], v[48:51]
	v_mfma_f32_16x16x32_bf16 v[36:39], v[136:139], v[172:175], v[36:39]
	v_mfma_f32_16x16x32_bf16 v[32:35], v[156:159], v[172:175], v[32:35]
	v_mfma_f32_16x16x32_bf16 v[20:23], v[136:139], v[180:183], v[20:23]
	v_mfma_f32_16x16x32_bf16 v[16:19], v[156:159], v[180:183], v[16:19]
	v_mfma_f32_16x16x32_bf16 v[4:7], v[136:139], v[202:205], v[4:7]
	v_mfma_f32_16x16x32_bf16 v[0:3], v[156:159], v[202:205], v[0:3]
	s_barrier
; #define PG8_STAGE(bufoff, gbase, voff) do { _Pragma("unroll") for (int _i = 0; _i < 2; ++_i) \
;         __builtin_amdgcn_global_load_lds((const unsigned*)((const char*)(gbase) + (voff)[_i]), (PG8_LAS unsigned*)(lds + (bufoff) + ldsw + _i * 8192), 16, 0, 0); } while (0)
; #define PG8_LDA(dst, b, h) do { _Pragma("unroll") for (int m = 0; m < 4; ++m) _Pragma("unroll") for (int k = 0; k < 2; ++k) dst[m][k] = *(const PG8_LAS bf16x8*)(lds + PG8_SA(b, h) + aoff + m * 2048 + k * 1024); } while (0)
; #define PG8_LDB(dst, b, h) do { _Pragma("unroll") for (int n = 0; n < 2; ++n) _Pragma("unroll") for (int k = 0; k < 2; ++k) dst[n][k] = *(const PG8_LAS bf16x8*)(lds + PG8_SB(b, h) + boff + n * 2048 + k * 1024); } while (0)
; #define PG8_MMA(ai, bj, At, Bt) do { __builtin_amdgcn_s_setprio(1); _Pragma("unroll") for (int m = 0; m < 4; ++m) _Pragma("unroll") for (int n = 0; n < 2; ++n) _Pragma("unroll") for (int k = 0; k < 2; ++k) \
;         acc[ai][bj][m][n] = __builtin_amdgcn_mfma_f32_16x16x32_bf16(Bt[n][k], At[m][k], acc[ai][bj][m][n], 0, 0, 0); __builtin_amdgcn_s_setprio(0); } while (0)
; template <class Epi, class Sched, bool ALIGN_EPI = false, bool SP2 = false>
; __device__ __forceinline__ void gemm_phase(PG8_LAS unsigned char* lds, const Gemm g, const Sched& S, const Epi& E) {
;     ...
;             PG8_LDB(B0, 0, 0); PG8_LDB(B1, 0, 1); PG8_SCHED; PG8_LDA(At, 0, 0); PG8_STAGE(PG8_SA(1, 1), a1 + hstep, voffA);
;             PG8_WAIT_V(8); PG8_WAIT_L(0); PG8_BAR; PG8_MMA(0, 0, At, B0); PG8_MMA(0, 1, At, B1); PG8_BAR; PG8_SCHED;
;             PG8_LDA(At, 0, 1); PG8_STAGE(PG8_SB(0, 0), b2, voffB); PG8_STAGE(PG8_SB(0, 1), b2 + hstep, voffB); PG8_STAGE(PG8_SA(0, 0), a2, voffA);
;             PG8_WAIT_V(8); PG8_WAIT_L(0); PG8_BAR; PG8_MMA(1, 0, At, B0); PG8_MMA(1, 1, At, B1); PG8_BAR; PG8_SCHED;
;             PG8_LDB(B0, 1, 0); PG8_LDB(B1, 1, 1); PG8_SCHED; PG8_LDA(At, 1, 0); PG8_STAGE(PG8_SA(0, 1), a2 + hstep, voffA);
;             PG8_WAIT_V(8); PG8_WAIT_L(0); PG8_BAR; PG8_MMA(0, 0, At, B0); PG8_MMA(0, 1, At, B1); PG8_BAR; PG8_SCHED;
;             PG8_LDA(At, 1, 1); PG8_STAGE(PG8_SB(1, 0), b3, voffB); PG8_STAGE(PG8_SB(1, 1), b3 + hstep, voffB); PG8_STAGE(PG8_SA(1, 0), a3, voffA);
;             PG8_WAIT_V(8); PG8_WAIT_L(0); PG8_BAR; PG8_MMA(1, 0, At, B0); PG8_MMA(1, 1, At, B1); PG8_BAR; PG8_SCHED;
;     ...
;         if constexpr (ALIGN_EPI) { if (wr == 0) PG8_BAR; }
	s_add_i32 s76, 0, 0x18000
	s_add_i32 s77, 0, 0x1c000
	v_add_u32_e32 v108, s76, v206
	v_add_u32_e32 v156, s77, v206
	ds_read_b128 v[80:83], v108
	ds_read_b128 v[84:87], v108 offset:1024
	ds_read_b128 v[104:107], v108 offset:2048
	ds_read_b128 v[108:111], v108 offset:3072
	ds_read_b128 v[128:131], v156
	ds_read_b128 v[136:139], v156 offset:1024
	ds_read_b128 v[152:155], v156 offset:2048
	ds_read_b128 v[156:159], v156 offset:3072
	s_add_u32 s64, s64, 0x4000
	s_addc_u32 s65, s65, 0
	s_mov_b32 m0, s50
	ds_read_b128 v[160:163], v207 offset:32768
	ds_read_b128 v[164:167], v207 offset:33792
	ds_read_b128 v[168:171], v207 offset:34816
	ds_read_b128 v[172:175], v207 offset:35840
	ds_read_b128 v[176:179], v207 offset:36864
	ds_read_b128 v[180:183], v207 offset:37888
	ds_read_b128 v[198:201], v207 offset:38912
	ds_read_b128 v[202:205], v207 offset:39936
	global_load_lds_dwordx4 v184, s[64:65]
	s_mov_b32 m0, s51
	s_nop 0
	global_load_lds_dwordx4 v188, s[64:65]
	s_waitcnt vmcnt(8)
	s_waitcnt lgkmcnt(0)
	s_barrier
	s_waitcnt lgkmcnt(0)
	v_mfma_f32_16x16x32_bf16 v[148:151], v[80:83], v[160:163], v[148:151]
	v_mfma_f32_16x16x32_bf16 v[144:147], v[104:107], v[160:163], v[144:147]
	v_mfma_f32_16x16x32_bf16 v[124:127], v[80:83], v[168:171], v[124:127]
	v_mfma_f32_16x16x32_bf16 v[120:123], v[104:107], v[168:171], v[120:123]
	v_mfma_f32_16x16x32_bf16 v[100:103], v[80:83], v[176:179], v[100:103]
	v_mfma_f32_16x16x32_bf16 v[96:99], v[104:107], v[176:179], v[96:99]
	v_mfma_f32_16x16x32_bf16 v[76:79], v[80:83], v[198:201], v[76:79]
	v_mfma_f32_16x16x32_bf16 v[72:75], v[104:107], v[198:201], v[72:75]
	v_mfma_f32_16x16x32_bf16 v[148:151], v[84:87], v[164:167], v[148:151]
	v_mfma_f32_16x16x32_bf16 v[144:147], v[108:111], v[164:167], v[144:147]
	v_mfma_f32_16x16x32_bf16 v[124:127], v[84:87], v[172:175], v[124:127]
	v_mfma_f32_16x16x32_bf16 v[120:123], v[108:111], v[172:175], v[120:123]
	v_mfma_f32_16x16x32_bf16 v[100:103], v[84:87], v[180:183], v[100:103]
	v_mfma_f32_16x16x32_bf16 v[96:99], v[108:111], v[180:183], v[96:99]
	v_mfma_f32_16x16x32_bf16 v[76:79], v[84:87], v[202:205], v[76:79]
	v_mfma_f32_16x16x32_bf16 v[72:75], v[108:111], v[202:205], v[72:75]
	v_mfma_f32_16x16x32_bf16 v[140:143], v[128:131], v[160:163], v[140:143]
	v_mfma_f32_16x16x32_bf16 v[132:135], v[152:155], v[160:163], v[132:135]
	v_mfma_f32_16x16x32_bf16 v[116:119], v[128:131], v[168:171], v[116:119]
	v_mfma_f32_16x16x32_bf16 v[112:115], v[152:155], v[168:171], v[112:115]
	v_mfma_f32_16x16x32_bf16 v[92:95], v[128:131], v[176:179], v[92:95]
	v_mfma_f32_16x16x32_bf16 v[88:91], v[152:155], v[176:179], v[88:91]
	v_mfma_f32_16x16x32_bf16 v[68:71], v[128:131], v[198:201], v[68:71]
	v_mfma_f32_16x16x32_bf16 v[64:67], v[152:155], v[198:201], v[64:67]
	v_mfma_f32_16x16x32_bf16 v[140:143], v[136:139], v[164:167], v[140:143]
	v_mfma_f32_16x16x32_bf16 v[132:135], v[156:159], v[164:167], v[132:135]
	v_mfma_f32_16x16x32_bf16 v[116:119], v[136:139], v[172:175], v[116:119]
	v_mfma_f32_16x16x32_bf16 v[112:115], v[156:159], v[172:175], v[112:115]
	v_mfma_f32_16x16x32_bf16 v[92:95], v[136:139], v[180:183], v[92:95]
	v_mfma_f32_16x16x32_bf16 v[88:91], v[156:159], v[180:183], v[88:91]
	v_mfma_f32_16x16x32_bf16 v[68:71], v[136:139], v[202:205], v[68:71]
	v_mfma_f32_16x16x32_bf16 v[64:67], v[156:159], v[202:205], v[64:67]
	s_barrier
	s_add_u32 s64, s20, 0x8000
	s_addc_u32 s65, s21, 0
	s_add_i32 s76, s76, s39
	s_mov_b32 m0, s76
	ds_read_b128 v[160:163], v207 offset:49152
	ds_read_b128 v[164:167], v207 offset:50176
	ds_read_b128 v[168:171], v207 offset:51200
	ds_read_b128 v[172:175], v207 offset:52224
	ds_read_b128 v[176:179], v207 offset:53248
	ds_read_b128 v[180:183], v207 offset:54272
	ds_read_b128 v[198:201], v207 offset:55296
	ds_read_b128 v[202:205], v207 offset:56320
	global_load_lds_dwordx4 v186, s[64:65]
	s_add_i32 m0, s76, 0x2000
	s_add_u32 s20, s20, 0xc000
	v_lshl_add_u64 v[208:209], s[64:65], 0, v[190:191]
	s_addc_u32 s21, s21, 0
	s_add_i32 s64, s77, s39
	global_load_lds_dwordx4 v[208:209], off
	s_mov_b32 m0, s64
	s_nop 0
	global_load_lds_dwordx4 v186, s[20:21]
	s_add_i32 m0, s64, 0x2000
	s_nop 0
	global_load_lds_dwordx4 v190, s[20:21]
	s_mov_b32 m0, s56
	s_nop 0
	global_load_lds_dwordx4 v184, s[18:19]
	s_mov_b32 m0, s57
	s_nop 0
	global_load_lds_dwordx4 v188, s[18:19]
	s_waitcnt vmcnt(8)
	s_waitcnt lgkmcnt(0)
	s_barrier
	s_waitcnt lgkmcnt(0)
	v_mfma_f32_16x16x32_bf16 v[60:63], v[80:83], v[160:163], v[60:63]
	v_mfma_f32_16x16x32_bf16 v[56:59], v[104:107], v[160:163], v[56:59]
	v_mfma_f32_16x16x32_bf16 v[44:47], v[80:83], v[168:171], v[44:47]
	v_mfma_f32_16x16x32_bf16 v[40:43], v[104:107], v[168:171], v[40:43]
	v_mfma_f32_16x16x32_bf16 v[28:31], v[80:83], v[176:179], v[28:31]
	v_mfma_f32_16x16x32_bf16 v[24:27], v[104:107], v[176:179], v[24:27]
	v_mfma_f32_16x16x32_bf16 v[12:15], v[80:83], v[198:201], v[12:15]
	v_mfma_f32_16x16x32_bf16 v[8:11], v[104:107], v[198:201], v[8:11]
	v_mfma_f32_16x16x32_bf16 v[60:63], v[84:87], v[164:167], v[60:63]
	v_mfma_f32_16x16x32_bf16 v[56:59], v[108:111], v[164:167], v[56:59]
	v_mfma_f32_16x16x32_bf16 v[44:47], v[84:87], v[172:175], v[44:47]
	v_mfma_f32_16x16x32_bf16 v[40:43], v[108:111], v[172:175], v[40:43]
	v_mfma_f32_16x16x32_bf16 v[28:31], v[84:87], v[180:183], v[28:31]
	v_mfma_f32_16x16x32_bf16 v[24:27], v[108:111], v[180:183], v[24:27]
	v_mfma_f32_16x16x32_bf16 v[12:15], v[84:87], v[202:205], v[12:15]
	v_mfma_f32_16x16x32_bf16 v[8:11], v[108:111], v[202:205], v[8:11]
	v_mfma_f32_16x16x32_bf16 v[52:55], v[128:131], v[160:163], v[52:55]
	v_mfma_f32_16x16x32_bf16 v[48:51], v[152:155], v[160:163], v[48:51]
	v_mfma_f32_16x16x32_bf16 v[36:39], v[128:131], v[168:171], v[36:39]
	v_mfma_f32_16x16x32_bf16 v[32:35], v[152:155], v[168:171], v[32:35]
	v_mfma_f32_16x16x32_bf16 v[20:23], v[128:131], v[176:179], v[20:23]
	v_mfma_f32_16x16x32_bf16 v[16:19], v[152:155], v[176:179], v[16:19]
	v_mfma_f32_16x16x32_bf16 v[4:7], v[128:131], v[198:201], v[4:7]
	v_mfma_f32_16x16x32_bf16 v[0:3], v[152:155], v[198:201], v[0:3]
	v_mfma_f32_16x16x32_bf16 v[52:55], v[136:139], v[164:167], v[52:55]
	v_mfma_f32_16x16x32_bf16 v[48:51], v[156:159], v[164:167], v[48:51]
	v_mfma_f32_16x16x32_bf16 v[36:39], v[136:139], v[172:175], v[36:39]
	v_mfma_f32_16x16x32_bf16 v[32:35], v[156:159], v[172:175], v[32:35]
	v_mfma_f32_16x16x32_bf16 v[20:23], v[136:139], v[180:183], v[20:23]
	v_mfma_f32_16x16x32_bf16 v[16:19], v[156:159], v[180:183], v[16:19]
	v_mfma_f32_16x16x32_bf16 v[4:7], v[136:139], v[202:205], v[4:7]
	v_mfma_f32_16x16x32_bf16 v[0:3], v[156:159], v[202:205], v[0:3]
	s_barrier
	s_add_u32 s16, s16, 0x10000
	s_addc_u32 s17, s17, 0
	s_add_u32 s66, s66, 0x10000
	s_addc_u32 s67, s67, 0
	s_cmp_ge_u32 s75, s53
	s_mov_b32 s18, s75
	s_cbranch_scc0 .LBB0_1322
	s_and_b64 vcc, exec, s[12:13]
	s_cbranch_vccz .LBB0_1325
	s_barrier

; #define PG8_STAGE(bufoff, gbase, voff) do { _Pragma("unroll") for (int _i = 0; _i < 2; ++_i) \
;         __builtin_amdgcn_global_load_lds((const unsigned*)((const char*)(gbase) + (voff)[_i]), (PG8_LAS unsigned*)(lds + (bufoff) + ldsw + _i * 8192), 16, 0, 0); } while (0)
; #define PG8_LDA(dst, b, h) do { _Pragma("unroll") for (int m = 0; m < 4; ++m) _Pragma("unroll") for (int k = 0; k < 2; ++k) dst[m][k] = *(const PG8_LAS bf16x8*)(lds + PG8_SA(b, h) + aoff + m * 2048 + k * 1024); } while (0)
; #define PG8_LDB(dst, b, h) do { _Pragma("unroll") for (int n = 0; n < 2; ++n) _Pragma("unroll") for (int k = 0; k < 2; ++k) dst[n][k] = *(const PG8_LAS bf16x8*)(lds + PG8_SB(b, h) + boff + n * 2048 + k * 1024); } while (0)
; template <class Epi, class Sched, bool ALIGN_EPI = false, bool SP2 = false>
; __device__ __forceinline__ void gemm_phase(PG8_LAS unsigned char* lds, const Gemm g, const Sched& S, const Epi& E) {
;     ...
;         for (int t = 0; t < nt; t += 2) {
;             const bool last = (t == nt - 2);
;             const char* a1 = cA + (size_t)(t + 1) * kstep;
;             const char* a2 = last ? nA : cA + (size_t)(t + 2) * kstep; const char* b2 = last ? nB : cB + (size_t)(t + 2) * kstep;
;             const char* a3 = a2 + kstep; const char* b3 = b2 + kstep;
;             if (last && has_next) S.a_ready(nxt);
;             if constexpr (SP2) {
;             PG8_LDB(B0, 0, 0); PG8_LDB(B1, 0, 1); PG8_SCHED; PG8_LDA(At, 0, 0); PG8_STAGE(PG8_SA(1, 1), a1 + hstep, voffA);
;             PG8_WAIT_V(8); PG8_WAIT_L(0); PG8_BAR; PG8_MMA(0, 0, At, B0); PG8_MMA(0, 1, At, B1); PG8_BAR; PG8_SCHED;
;             PG8_LDA(At, 0, 1); PG8_STAGE(PG8_SB(0, 0), b2, voffB); PG8_STAGE(PG8_SB(0, 1), b2 + hstep, voffB); PG8_STAGE(PG8_SA(0, 0), a2, voffA);
;             PG8_WAIT_V(8); PG8_WAIT_L(0); PG8_BAR; PG8_MMA(1, 0, At, B0); PG8_MMA(1, 1, At, B1); PG8_BAR; PG8_SCHED;
;             PG8_LDB(B0, 1, 0); PG8_LDB(B1, 1, 1); PG8_SCHED; PG8_LDA(At, 1, 0); PG8_STAGE(PG8_SA(0, 1), a2 + hstep, voffA);
;             PG8_WAIT_V(8); PG8_WAIT_L(0); PG8_BAR; PG8_MMA(0, 0, At, B0); PG8_MMA(0, 1, At, B1); PG8_BAR; PG8_SCHED;
;             PG8_LDA(At, 1, 1); PG8_STAGE(PG8_SB(1, 0), b3, voffB); PG8_STAGE(PG8_SB(1, 1), b3 + hstep, voffB); PG8_STAGE(PG8_SA(1, 0), a3, voffA);
;             PG8_WAIT_V(8); PG8_WAIT_L(0); PG8_BAR; PG8_MMA(1, 0, At, B0); PG8_MMA(1, 1, At, B1); PG8_BAR; PG8_SCHED;
.LBB0_1356:
	s_add_u32 s20, s18, 0x4000
	s_addc_u32 s21, s19, 0
	s_cmp_eq_u32 s68, 12
	s_cselect_b32 s64, s40, s20
	s_cselect_b32 s65, s11, s21
	s_cselect_b32 s62, s61, s66
	s_cselect_b32 s63, s9, s67
	s_add_u32 s20, s64, 0x8000
	s_addc_u32 s21, s65, 0
	s_add_i32 s69, 0, 0x10000
	s_add_i32 s72, 0, 0x14000
	v_add_u32_e32 v140, s69, v162
	v_add_u32_e32 v160, s72, v162
	ds_read_b128 v[128:131], v140
	ds_read_b128 v[132:135], v140 offset:1024
	ds_read_b128 v[136:139], v140 offset:2048
	ds_read_b128 v[140:143], v140 offset:3072
	ds_read_b128 v[156:159], v160
	ds_read_b128 v[164:167], v160 offset:1024
	ds_read_b128 v[168:171], v160 offset:2048
	ds_read_b128 v[172:175], v160 offset:3072
	s_add_i32 m0, s37, 0xc000
	ds_read_b128 v[176:179], v163
	ds_read_b128 v[180:183], v163 offset:1024
	ds_read_b128 v[184:187], v163 offset:2048
	ds_read_b128 v[188:191], v163 offset:3072
	ds_read_b128 v[192:195], v163 offset:4096
	ds_read_b128 v[196:199], v163 offset:5120
	ds_read_b128 v[200:203], v163 offset:6144
	ds_read_b128 v[204:207], v163 offset:7168
	global_load_lds_dwordx4 v152, s[18:19]
	s_add_i32 m0, s37, 0xe000
	s_nop 0
	global_load_lds_dwordx4 v154, s[18:19]
	s_waitcnt vmcnt(8)
	s_waitcnt lgkmcnt(0)
	s_barrier
	s_waitcnt lgkmcnt(0)
	v_mfma_f32_16x16x32_bf16 v[124:127], v[128:131], v[176:179], v[124:127]
	v_mfma_f32_16x16x32_bf16 v[120:123], v[136:139], v[176:179], v[120:123]
	v_mfma_f32_16x16x32_bf16 v[108:111], v[128:131], v[184:187], v[108:111]
	v_mfma_f32_16x16x32_bf16 v[104:107], v[136:139], v[184:187], v[104:107]
	v_mfma_f32_16x16x32_bf16 v[92:95], v[128:131], v[192:195], v[92:95]
	v_mfma_f32_16x16x32_bf16 v[88:91], v[136:139], v[192:195], v[88:91]
	v_mfma_f32_16x16x32_bf16 v[76:79], v[128:131], v[200:203], v[76:79]
	v_mfma_f32_16x16x32_bf16 v[72:75], v[136:139], v[200:203], v[72:75]
	v_mfma_f32_16x16x32_bf16 v[124:127], v[132:135], v[180:183], v[124:127]
	v_mfma_f32_16x16x32_bf16 v[120:123], v[140:143], v[180:183], v[120:123]
	v_mfma_f32_16x16x32_bf16 v[108:111], v[132:135], v[188:191], v[108:111]
	v_mfma_f32_16x16x32_bf16 v[104:107], v[140:143], v[188:191], v[104:107]
	v_mfma_f32_16x16x32_bf16 v[92:95], v[132:135], v[196:199], v[92:95]
	v_mfma_f32_16x16x32_bf16 v[88:91], v[140:143], v[196:199], v[88:91]
	v_mfma_f32_16x16x32_bf16 v[76:79], v[132:135], v[204:207], v[76:79]
	v_mfma_f32_16x16x32_bf16 v[72:75], v[140:143], v[204:207], v[72:75]
	v_mfma_f32_16x16x32_bf16 v[116:119], v[156:159], v[176:179], v[116:119]
	v_mfma_f32_16x16x32_bf16 v[112:115], v[168:171], v[176:179], v[112:115]
	v_mfma_f32_16x16x32_bf16 v[100:103], v[156:159], v[184:187], v[100:103]
	v_mfma_f32_16x16x32_bf16 v[96:99], v[168:171], v[184:187], v[96:99]
	v_mfma_f32_16x16x32_bf16 v[84:87], v[156:159], v[192:195], v[84:87]
	v_mfma_f32_16x16x32_bf16 v[80:83], v[168:171], v[192:195], v[80:83]
	v_mfma_f32_16x16x32_bf16 v[68:71], v[156:159], v[200:203], v[68:71]
	v_mfma_f32_16x16x32_bf16 v[64:67], v[168:171], v[200:203], v[64:67]
	v_mfma_f32_16x16x32_bf16 v[116:119], v[164:167], v[180:183], v[116:119]
	v_mfma_f32_16x16x32_bf16 v[112:115], v[172:175], v[180:183], v[112:115]
	v_mfma_f32_16x16x32_bf16 v[100:103], v[164:167], v[188:191], v[100:103]
	v_mfma_f32_16x16x32_bf16 v[96:99], v[172:175], v[188:191], v[96:99]
	v_mfma_f32_16x16x32_bf16 v[84:87], v[164:167], v[196:199], v[84:87]
	v_mfma_f32_16x16x32_bf16 v[80:83], v[172:175], v[196:199], v[80:83]
	v_mfma_f32_16x16x32_bf16 v[68:71], v[164:167], v[204:207], v[68:71]
	v_mfma_f32_16x16x32_bf16 v[64:67], v[172:175], v[204:207], v[64:67]
	s_barrier
	s_add_i32 s69, s69, s30
	s_mov_b32 m0, s69
	ds_read_b128 v[176:179], v163 offset:16384
	ds_read_b128 v[180:183], v163 offset:17408
	ds_read_b128 v[184:187], v163 offset:18432
	ds_read_b128 v[188:191], v163 offset:19456
	ds_read_b128 v[192:195], v163 offset:20480
	ds_read_b128 v[196:199], v163 offset:21504
	ds_read_b128 v[200:203], v163 offset:22528
	ds_read_b128 v[204:207], v163 offset:23552
	global_load_lds_dwordx4 v148, s[62:63]
	s_add_i32 m0, s69, 0x2000
	s_add_u32 s70, s62, 0x4000
	s_addc_u32 s71, s63, 0
	s_add_i32 s69, s72, s30
	global_load_lds_dwordx4 v144, s[62:63]
	s_mov_b32 m0, s69
	s_nop 0
	global_load_lds_dwordx4 v148, s[70:71]
	s_add_i32 m0, s69, 0x2000
	s_nop 0
	global_load_lds_dwordx4 v144, s[70:71]
	s_mov_b32 m0, s37
	s_nop 0
	global_load_lds_dwordx4 v150, s[64:65]
	s_mov_b32 m0, s39
	s_nop 0
	global_load_lds_dwordx4 v146, s[64:65]
	s_waitcnt vmcnt(8)
	s_waitcnt lgkmcnt(0)
	s_barrier
	s_waitcnt lgkmcnt(0)
	v_mfma_f32_16x16x32_bf16 v[60:63], v[128:131], v[176:179], v[60:63]
	v_mfma_f32_16x16x32_bf16 v[56:59], v[136:139], v[176:179], v[56:59]
	v_mfma_f32_16x16x32_bf16 v[44:47], v[128:131], v[184:187], v[44:47]
	v_mfma_f32_16x16x32_bf16 v[40:43], v[136:139], v[184:187], v[40:43]
	v_mfma_f32_16x16x32_bf16 v[28:31], v[128:131], v[192:195], v[28:31]
	v_mfma_f32_16x16x32_bf16 v[24:27], v[136:139], v[192:195], v[24:27]
	v_mfma_f32_16x16x32_bf16 v[12:15], v[128:131], v[200:203], v[12:15]
	v_mfma_f32_16x16x32_bf16 v[8:11], v[136:139], v[200:203], v[8:11]
	v_mfma_f32_16x16x32_bf16 v[60:63], v[132:135], v[180:183], v[60:63]
	v_mfma_f32_16x16x32_bf16 v[56:59], v[140:143], v[180:183], v[56:59]
	v_mfma_f32_16x16x32_bf16 v[44:47], v[132:135], v[188:191], v[44:47]
	v_mfma_f32_16x16x32_bf16 v[40:43], v[140:143], v[188:191], v[40:43]
	v_mfma_f32_16x16x32_bf16 v[28:31], v[132:135], v[196:199], v[28:31]
	v_mfma_f32_16x16x32_bf16 v[24:27], v[140:143], v[196:199], v[24:27]
	v_mfma_f32_16x16x32_bf16 v[12:15], v[132:135], v[204:207], v[12:15]
	v_mfma_f32_16x16x32_bf16 v[8:11], v[140:143], v[204:207], v[8:11]
	v_mfma_f32_16x16x32_bf16 v[52:55], v[156:159], v[176:179], v[52:55]
	v_mfma_f32_16x16x32_bf16 v[48:51], v[168:171], v[176:179], v[48:51]
	v_mfma_f32_16x16x32_bf16 v[36:39], v[156:159], v[184:187], v[36:39]
	v_mfma_f32_16x16x32_bf16 v[32:35], v[168:171], v[184:187], v[32:35]
	v_mfma_f32_16x16x32_bf16 v[20:23], v[156:159], v[192:195], v[20:23]
	v_mfma_f32_16x16x32_bf16 v[16:19], v[168:171], v[192:195], v[16:19]
	v_mfma_f32_16x16x32_bf16 v[4:7], v[156:159], v[200:203], v[4:7]
	v_mfma_f32_16x16x32_bf16 v[0:3], v[168:171], v[200:203], v[0:3]
	v_mfma_f32_16x16x32_bf16 v[52:55], v[164:167], v[180:183], v[52:55]
	v_mfma_f32_16x16x32_bf16 v[48:51], v[172:175], v[180:183], v[48:51]
	v_mfma_f32_16x16x32_bf16 v[36:39], v[164:167], v[188:191], v[36:39]
	v_mfma_f32_16x16x32_bf16 v[32:35], v[172:175], v[188:191], v[32:35]
	v_mfma_f32_16x16x32_bf16 v[20:23], v[164:167], v[196:199], v[20:23]
	v_mfma_f32_16x16x32_bf16 v[16:19], v[172:175], v[196:199], v[16:19]
	v_mfma_f32_16x16x32_bf16 v[4:7], v[164:167], v[204:207], v[4:7]
	v_mfma_f32_16x16x32_bf16 v[0:3], v[172:175], v[204:207], v[0:3]
	s_barrier
; #define PG8_STAGE(bufoff, gbase, voff) do { _Pragma("unroll") for (int _i = 0; _i < 2; ++_i) \
;         __builtin_amdgcn_global_load_lds((const unsigned*)((const char*)(gbase) + (voff)[_i]), (PG8_LAS unsigned*)(lds + (bufoff) + ldsw + _i * 8192), 16, 0, 0); } while (0)
; #define PG8_LDA(dst, b, h) do { _Pragma("unroll") for (int m = 0; m < 4; ++m) _Pragma("unroll") for (int k = 0; k < 2; ++k) dst[m][k] = *(const PG8_LAS bf16x8*)(lds + PG8_SA(b, h) + aoff + m * 2048 + k * 1024); } while (0)
; #define PG8_LDB(dst, b, h) do { _Pragma("unroll") for (int n = 0; n < 2; ++n) _Pragma("unroll") for (int k = 0; k < 2; ++k) dst[n][k] = *(const PG8_LAS bf16x8*)(lds + PG8_SB(b, h) + boff + n * 2048 + k * 1024); } while (0)
; #define PG8_MMA(ai, bj, At, Bt) do { __builtin_amdgcn_s_setprio(1); _Pragma("unroll") for (int m = 0; m < 4; ++m) _Pragma("unroll") for (int n = 0; n < 2; ++n) _Pragma("unroll") for (int k = 0; k < 2; ++k) \
;         acc[ai][bj][m][n] = __builtin_amdgcn_mfma_f32_16x16x32_bf16(Bt[n][k], At[m][k], acc[ai][bj][m][n], 0, 0, 0); __builtin_amdgcn_s_setprio(0); } while (0)
; template <class Epi, class Sched, bool ALIGN_EPI = false, bool SP2 = false>
; __device__ __forceinline__ void gemm_phase(PG8_LAS unsigned char* lds, const Gemm g, const Sched& S, const Epi& E) {
;     ...
;             PG8_LDB(B0, 0, 0); PG8_LDB(B1, 0, 1); PG8_SCHED; PG8_LDA(At, 0, 0); PG8_STAGE(PG8_SA(1, 1), a1 + hstep, voffA);
;             PG8_WAIT_V(8); PG8_WAIT_L(0); PG8_BAR; PG8_MMA(0, 0, At, B0); PG8_MMA(0, 1, At, B1); PG8_BAR; PG8_SCHED;
;             PG8_LDA(At, 0, 1); PG8_STAGE(PG8_SB(0, 0), b2, voffB); PG8_STAGE(PG8_SB(0, 1), b2 + hstep, voffB); PG8_STAGE(PG8_SA(0, 0), a2, voffA);
;             PG8_WAIT_V(8); PG8_WAIT_L(0); PG8_BAR; PG8_MMA(1, 0, At, B0); PG8_MMA(1, 1, At, B1); PG8_BAR; PG8_SCHED;
;             PG8_LDB(B0, 1, 0); PG8_LDB(B1, 1, 1); PG8_SCHED; PG8_LDA(At, 1, 0); PG8_STAGE(PG8_SA(0, 1), a2 + hstep, voffA);
;             PG8_WAIT_V(8); PG8_WAIT_L(0); PG8_BAR; PG8_MMA(0, 0, At, B0); PG8_MMA(0, 1, At, B1); PG8_BAR; PG8_SCHED;
;             PG8_LDA(At, 1, 1); PG8_STAGE(PG8_SB(1, 0), b3, voffB); PG8_STAGE(PG8_SB(1, 1), b3 + hstep, voffB); PG8_STAGE(PG8_SA(1, 0), a3, voffA);
;             PG8_WAIT_V(8); PG8_WAIT_L(0); PG8_BAR; PG8_MMA(1, 0, At, B0); PG8_MMA(1, 1, At, B1); PG8_BAR; PG8_SCHED;
;     ...
;         if constexpr (ALIGN_EPI) { if (wr == 0) PG8_BAR; }
	s_add_i32 s69, 0, 0x18000
	s_add_i32 s70, 0, 0x1c000
	v_add_u32_e32 v140, s69, v162
	v_add_u32_e32 v160, s70, v162
	ds_read_b128 v[128:131], v140
	ds_read_b128 v[132:135], v140 offset:1024
	ds_read_b128 v[136:139], v140 offset:2048
	ds_read_b128 v[140:143], v140 offset:3072
	ds_read_b128 v[156:159], v160
	ds_read_b128 v[164:167], v160 offset:1024
	ds_read_b128 v[168:171], v160 offset:2048
	ds_read_b128 v[172:175], v160 offset:3072
	s_add_u32 s64, s64, 0x4000
	s_addc_u32 s65, s65, 0
	s_mov_b32 m0, s41
	ds_read_b128 v[176:179], v163 offset:32768
	ds_read_b128 v[180:183], v163 offset:33792
	ds_read_b128 v[184:187], v163 offset:34816
	ds_read_b128 v[188:191], v163 offset:35840
	ds_read_b128 v[192:195], v163 offset:36864
	ds_read_b128 v[196:199], v163 offset:37888
	ds_read_b128 v[200:203], v163 offset:38912
	ds_read_b128 v[204:207], v163 offset:39936
	global_load_lds_dwordx4 v150, s[64:65]
	s_mov_b32 m0, s42
	s_nop 0
	global_load_lds_dwordx4 v146, s[64:65]
	s_waitcnt vmcnt(8)
	s_waitcnt lgkmcnt(0)
	s_barrier
	s_waitcnt lgkmcnt(0)
	v_mfma_f32_16x16x32_bf16 v[124:127], v[128:131], v[176:179], v[124:127]
	v_mfma_f32_16x16x32_bf16 v[120:123], v[136:139], v[176:179], v[120:123]
	v_mfma_f32_16x16x32_bf16 v[108:111], v[128:131], v[184:187], v[108:111]
	v_mfma_f32_16x16x32_bf16 v[104:107], v[136:139], v[184:187], v[104:107]
	v_mfma_f32_16x16x32_bf16 v[92:95], v[128:131], v[192:195], v[92:95]
	v_mfma_f32_16x16x32_bf16 v[88:91], v[136:139], v[192:195], v[88:91]
	v_mfma_f32_16x16x32_bf16 v[76:79], v[128:131], v[200:203], v[76:79]
	v_mfma_f32_16x16x32_bf16 v[72:75], v[136:139], v[200:203], v[72:75]
	v_mfma_f32_16x16x32_bf16 v[124:127], v[132:135], v[180:183], v[124:127]
	v_mfma_f32_16x16x32_bf16 v[120:123], v[140:143], v[180:183], v[120:123]
	v_mfma_f32_16x16x32_bf16 v[108:111], v[132:135], v[188:191], v[108:111]
	v_mfma_f32_16x16x32_bf16 v[104:107], v[140:143], v[188:191], v[104:107]
	v_mfma_f32_16x16x32_bf16 v[92:95], v[132:135], v[196:199], v[92:95]
	v_mfma_f32_16x16x32_bf16 v[88:91], v[140:143], v[196:199], v[88:91]
	v_mfma_f32_16x16x32_bf16 v[76:79], v[132:135], v[204:207], v[76:79]
	v_mfma_f32_16x16x32_bf16 v[72:75], v[140:143], v[204:207], v[72:75]
	v_mfma_f32_16x16x32_bf16 v[116:119], v[156:159], v[176:179], v[116:119]
	v_mfma_f32_16x16x32_bf16 v[112:115], v[168:171], v[176:179], v[112:115]
	v_mfma_f32_16x16x32_bf16 v[100:103], v[156:159], v[184:187], v[100:103]
	v_mfma_f32_16x16x32_bf16 v[96:99], v[168:171], v[184:187], v[96:99]
	v_mfma_f32_16x16x32_bf16 v[84:87], v[156:159], v[192:195], v[84:87]
	v_mfma_f32_16x16x32_bf16 v[80:83], v[168:171], v[192:195], v[80:83]
	v_mfma_f32_16x16x32_bf16 v[68:71], v[156:159], v[200:203], v[68:71]
	v_mfma_f32_16x16x32_bf16 v[64:67], v[168:171], v[200:203], v[64:67]
	v_mfma_f32_16x16x32_bf16 v[116:119], v[164:167], v[180:183], v[116:119]
	v_mfma_f32_16x16x32_bf16 v[112:115], v[172:175], v[180:183], v[112:115]
	v_mfma_f32_16x16x32_bf16 v[100:103], v[164:167], v[188:191], v[100:103]
	v_mfma_f32_16x16x32_bf16 v[96:99], v[172:175], v[188:191], v[96:99]
	v_mfma_f32_16x16x32_bf16 v[84:87], v[164:167], v[196:199], v[84:87]
	v_mfma_f32_16x16x32_bf16 v[80:83], v[172:175], v[196:199], v[80:83]
	v_mfma_f32_16x16x32_bf16 v[68:71], v[164:167], v[204:207], v[68:71]
	v_mfma_f32_16x16x32_bf16 v[64:67], v[172:175], v[204:207], v[64:67]
	s_barrier
	s_add_u32 s64, s62, 0x8000
	s_addc_u32 s65, s63, 0
	s_add_i32 s69, s69, s30
	s_mov_b32 m0, s69
	ds_read_b128 v[176:179], v163 offset:49152
	ds_read_b128 v[180:183], v163 offset:50176
	ds_read_b128 v[184:187], v163 offset:51200
	ds_read_b128 v[188:191], v163 offset:52224
	ds_read_b128 v[192:195], v163 offset:53248
	ds_read_b128 v[196:199], v163 offset:54272
	ds_read_b128 v[200:203], v163 offset:55296
	ds_read_b128 v[204:207], v163 offset:56320
	global_load_lds_dwordx4 v148, s[64:65]
	s_add_i32 m0, s69, 0x2000
	s_add_u32 s62, s62, 0xc000
	v_lshl_add_u64 v[160:161], s[64:65], 0, v[144:145]
	s_addc_u32 s63, s63, 0
	s_add_i32 s64, s70, s30
	global_load_lds_dwordx4 v[160:161], off
	s_mov_b32 m0, s64
	s_nop 0
	global_load_lds_dwordx4 v148, s[62:63]
	s_add_i32 m0, s64, 0x2000
	s_nop 0
	global_load_lds_dwordx4 v144, s[62:63]
	s_mov_b32 m0, s54
	s_nop 0
	global_load_lds_dwordx4 v150, s[20:21]
	s_mov_b32 m0, s55
	s_nop 0
	global_load_lds_dwordx4 v146, s[20:21]
	s_waitcnt vmcnt(8)
	s_waitcnt lgkmcnt(0)
	s_barrier
	s_waitcnt lgkmcnt(0)
	v_mfma_f32_16x16x32_bf16 v[60:63], v[128:131], v[176:179], v[60:63]
	v_mfma_f32_16x16x32_bf16 v[56:59], v[136:139], v[176:179], v[56:59]
	v_mfma_f32_16x16x32_bf16 v[44:47], v[128:131], v[184:187], v[44:47]
	v_mfma_f32_16x16x32_bf16 v[40:43], v[136:139], v[184:187], v[40:43]
	v_mfma_f32_16x16x32_bf16 v[28:31], v[128:131], v[192:195], v[28:31]
	v_mfma_f32_16x16x32_bf16 v[24:27], v[136:139], v[192:195], v[24:27]
	v_mfma_f32_16x16x32_bf16 v[12:15], v[128:131], v[200:203], v[12:15]
	v_mfma_f32_16x16x32_bf16 v[8:11], v[136:139], v[200:203], v[8:11]
	v_mfma_f32_16x16x32_bf16 v[60:63], v[132:135], v[180:183], v[60:63]
	v_mfma_f32_16x16x32_bf16 v[56:59], v[140:143], v[180:183], v[56:59]
	v_mfma_f32_16x16x32_bf16 v[44:47], v[132:135], v[188:191], v[44:47]
	v_mfma_f32_16x16x32_bf16 v[40:43], v[140:143], v[188:191], v[40:43]
	v_mfma_f32_16x16x32_bf16 v[28:31], v[132:135], v[196:199], v[28:31]
	v_mfma_f32_16x16x32_bf16 v[24:27], v[140:143], v[196:199], v[24:27]
	v_mfma_f32_16x16x32_bf16 v[12:15], v[132:135], v[204:207], v[12:15]
	v_mfma_f32_16x16x32_bf16 v[8:11], v[140:143], v[204:207], v[8:11]
	v_mfma_f32_16x16x32_bf16 v[52:55], v[156:159], v[176:179], v[52:55]
	v_mfma_f32_16x16x32_bf16 v[48:51], v[168:171], v[176:179], v[48:51]
	v_mfma_f32_16x16x32_bf16 v[36:39], v[156:159], v[184:187], v[36:39]
	v_mfma_f32_16x16x32_bf16 v[32:35], v[168:171], v[184:187], v[32:35]
	v_mfma_f32_16x16x32_bf16 v[20:23], v[156:159], v[192:195], v[20:23]
	v_mfma_f32_16x16x32_bf16 v[16:19], v[168:171], v[192:195], v[16:19]
	v_mfma_f32_16x16x32_bf16 v[4:7], v[156:159], v[200:203], v[4:7]
	v_mfma_f32_16x16x32_bf16 v[0:3], v[168:171], v[200:203], v[0:3]
	v_mfma_f32_16x16x32_bf16 v[52:55], v[164:167], v[180:183], v[52:55]
	v_mfma_f32_16x16x32_bf16 v[48:51], v[172:175], v[180:183], v[48:51]
	v_mfma_f32_16x16x32_bf16 v[36:39], v[164:167], v[188:191], v[36:39]
	v_mfma_f32_16x16x32_bf16 v[32:35], v[172:175], v[188:191], v[32:35]
	v_mfma_f32_16x16x32_bf16 v[20:23], v[164:167], v[196:199], v[20:23]
	v_mfma_f32_16x16x32_bf16 v[16:19], v[172:175], v[196:199], v[16:19]
	v_mfma_f32_16x16x32_bf16 v[4:7], v[164:167], v[204:207], v[4:7]
	v_mfma_f32_16x16x32_bf16 v[0:3], v[172:175], v[204:207], v[0:3]
	s_barrier
	s_add_i32 s68, s68, 2
	s_add_u32 s18, s18, 0x10000
	s_addc_u32 s19, s19, 0
	s_add_u32 s66, s66, 0x10000
	s_addc_u32 s67, s67, 0
	s_cmp_gt_u32 s68, 13
	s_cbranch_scc0 .LBB0_1356
	s_and_b64 vcc, exec, s[6:7]
	s_cbranch_vccz .LBB0_1359
	s_barrier
